# mix epilogue hand-written: 16-byte HG/MX accesses via permlane16 swap, 8 groups in flight; attn dequeue prefetch; top-k ballots over rotating SGPR pairs
# speedup vs baseline: 1.1966x; 1.0327x over previous
.LBB0_71:
	s_xor_b64 s[12:13], s[4:5], -1
	s_and_b64 s[16:17], s[4:5], exec
	s_mov_b32 s16, 0x1a580000
	s_cselect_b32 s26, s16, 0xa180000
	s_add_u32 s28, s8, s26
	s_addc_u32 s29, s9, 0
	s_and_b64 s[4:5], s[4:5], exec
	s_mov_b32 s4, 0xb00000
	s_cselect_b32 s30, s4, 0xc00000
	s_add_u32 s31, s8, s30
	s_addc_u32 s34, s9, 0
	s_lshl_b64 s[0:1], s[0:1], 1
	s_add_u32 s16, s24, s0
	s_mov_b32 s27, 0
	s_addc_u32 s17, s25, s1
	s_branch .LBB0_74
.LBB0_73:
	s_and_b64 vcc, exec, s[0:1]
	s_cbranch_vccnz .LBB0_70

.LBB0_83:
	s_or_b64 exec, exec, s[18:19]
	v_lshrrev_b32_e32 v212, 6, v211
	v_lshrrev_b32_e32 v214, 2, v212
	v_and_b32_e32 v212, 3, v212
	v_lshlrev_b32_e32 v214, 6, v214
	v_and_b32_e32 v246, 15, v219
	v_add3_u32 v214, v214, v246, s4
	v_lshrrev_b32_e32 v246, 4, v219
	v_and_b32_e32 v247, 1, v246
	v_lshrrev_b32_e32 v246, 1, v246
	v_lshl_add_u32 v246, v247, 1, v246
	v_lshlrev_b32_e32 v246, 4, v246
	v_lshl_add_u32 v246, v212, 6, v246
	s_lshl_b32 s42, s0, 1
	v_add_u32_e32 v246, s42, v246
	v_mov_b32_e32 v247, 0
	s_mov_b32 s43, 0
	v_mov_b32_e32 v216, v214
	v_mov_b32_e32 v217, 0
	v_lshlrev_b64 v[144:145], 12, v[216:217]
	v_lshlrev_b64 v[146:147], 11, v[216:217]
	v_lshl_add_u64 v[144:145], v[144:145], 0, v[246:247]
	v_lshl_add_u64 v[146:147], v[146:147], 0, v[246:247]
	v_lshl_add_u64 v[144:145], v[144:145], 0, s[16:17]
	v_lshl_add_u64 v[146:147], v[146:147], 0, s[10:11]
	s_and_b64 vcc, exec, s[12:13]
	s_cbranch_vccnz .Lmix_pass1
	s_mov_b32 s42, 0x0
	v_lshl_add_u64 v[148:149], v[144:145], 0, s[42:43]
	global_load_dwordx4 v[166:169], v[148:149], off offset:0
	s_mov_b32 s42, 0x0
	v_lshl_add_u64 v[150:151], v[146:147], 0, s[42:43]
	s_mov_b32 s42, 0x10000
	v_lshl_add_u64 v[148:149], v[144:145], 0, s[42:43]
	global_load_dwordx4 v[170:173], v[148:149], off offset:0
	s_mov_b32 s42, 0x8000
	v_lshl_add_u64 v[152:153], v[146:147], 0, s[42:43]
	s_mov_b32 s42, 0x20000
	v_lshl_add_u64 v[148:149], v[144:145], 0, s[42:43]
	global_load_dwordx4 v[174:177], v[148:149], off offset:0
	s_mov_b32 s42, 0x10000
	v_lshl_add_u64 v[154:155], v[146:147], 0, s[42:43]
	s_mov_b32 s42, 0x30000
	v_lshl_add_u64 v[148:149], v[144:145], 0, s[42:43]
	global_load_dwordx4 v[178:181], v[148:149], off offset:0
	s_mov_b32 s42, 0x18000
	v_lshl_add_u64 v[156:157], v[146:147], 0, s[42:43]
	s_mov_b32 s42, 0x0
	v_lshl_add_u64 v[148:149], v[144:145], 0, s[42:43]
	global_load_dwordx4 v[182:185], v[148:149], off offset:256
	s_mov_b32 s42, 0x0
	v_lshl_add_u64 v[158:159], v[146:147], 0, s[42:43]
	s_mov_b32 s42, 0x10000
	v_lshl_add_u64 v[148:149], v[144:145], 0, s[42:43]
	global_load_dwordx4 v[186:189], v[148:149], off offset:256
	s_mov_b32 s42, 0x8000
	v_lshl_add_u64 v[160:161], v[146:147], 0, s[42:43]
	s_mov_b32 s42, 0x20000
	v_lshl_add_u64 v[148:149], v[144:145], 0, s[42:43]
	global_load_dwordx4 v[190:193], v[148:149], off offset:256
	s_mov_b32 s42, 0x10000
	v_lshl_add_u64 v[162:163], v[146:147], 0, s[42:43]
	s_mov_b32 s42, 0x30000
	v_lshl_add_u64 v[148:149], v[144:145], 0, s[42:43]
	global_load_dwordx4 v[194:197], v[148:149], off offset:256
	s_mov_b32 s42, 0x18000
	v_lshl_add_u64 v[164:165], v[146:147], 0, s[42:43]
	s_waitcnt vmcnt(7)
	v_permlane16_swap_b32_e32 v166, v168
	v_permlane16_swap_b32_e32 v167, v169
	v_lshlrev_b32_e32 v246, 16, v166
	v_and_b32_e32 v247, 0xffff0000, v166
	v_lshlrev_b32_e32 v248, 16, v167
	v_and_b32_e32 v249, 0xffff0000, v167
	v_pk_mul_f32 v[246:247], v[126:127], v[246:247]
	v_pk_mul_f32 v[248:249], v[128:129], v[248:249]
	v_cvt_pk_bf16_f32 v166, v246, v247
	v_cvt_pk_bf16_f32 v167, v248, v249
	v_lshlrev_b32_e32 v246, 16, v168
	v_and_b32_e32 v247, 0xffff0000, v168
	v_lshlrev_b32_e32 v248, 16, v169
	v_and_b32_e32 v249, 0xffff0000, v169
	v_pk_mul_f32 v[246:247], v[122:123], v[246:247]
	v_pk_mul_f32 v[248:249], v[124:125], v[248:249]
	v_cvt_pk_bf16_f32 v168, v246, v247
	v_cvt_pk_bf16_f32 v169, v248, v249
	s_nop 1
	v_permlane16_swap_b32_e32 v166, v168
	v_permlane16_swap_b32_e32 v167, v169
	global_store_dwordx4 v[150:151], v[166:169], off offset:0
	s_nop 0
	s_mov_b32 s42, 0x80000
	v_lshl_add_u64 v[148:149], v[144:145], 0, s[42:43]
	global_load_dwordx4 v[166:169], v[148:149], off offset:0
	s_mov_b32 s42, 0x40000
	v_lshl_add_u64 v[150:151], v[146:147], 0, s[42:43]
	s_waitcnt vmcnt(8)
	v_permlane16_swap_b32_e32 v170, v172
	v_permlane16_swap_b32_e32 v171, v173
	v_lshlrev_b32_e32 v246, 16, v170
	v_and_b32_e32 v247, 0xffff0000, v170
	v_lshlrev_b32_e32 v248, 16, v171
	v_and_b32_e32 v249, 0xffff0000, v171
	v_pk_mul_f32 v[246:247], v[118:119], v[246:247]
	v_pk_mul_f32 v[248:249], v[120:121], v[248:249]
	v_cvt_pk_bf16_f32 v170, v246, v247
	v_cvt_pk_bf16_f32 v171, v248, v249
	v_lshlrev_b32_e32 v246, 16, v172
	v_and_b32_e32 v247, 0xffff0000, v172
	v_lshlrev_b32_e32 v248, 16, v173
	v_and_b32_e32 v249, 0xffff0000, v173
	v_pk_mul_f32 v[246:247], v[114:115], v[246:247]
	v_pk_mul_f32 v[248:249], v[116:117], v[248:249]
	v_cvt_pk_bf16_f32 v172, v246, v247
	v_cvt_pk_bf16_f32 v173, v248, v249
	s_nop 1
	v_permlane16_swap_b32_e32 v170, v172
	v_permlane16_swap_b32_e32 v171, v173
	global_store_dwordx4 v[152:153], v[170:173], off offset:0
	s_nop 0
	s_mov_b32 s42, 0x90000
	v_lshl_add_u64 v[148:149], v[144:145], 0, s[42:43]
	global_load_dwordx4 v[170:173], v[148:149], off offset:0
	s_mov_b32 s42, 0x48000
	v_lshl_add_u64 v[152:153], v[146:147], 0, s[42:43]
	s_waitcnt vmcnt(9)
	v_permlane16_swap_b32_e32 v174, v176
	v_permlane16_swap_b32_e32 v175, v177
	v_lshlrev_b32_e32 v246, 16, v174
	v_and_b32_e32 v247, 0xffff0000, v174
	v_lshlrev_b32_e32 v248, 16, v175
	v_and_b32_e32 v249, 0xffff0000, v175
	v_pk_mul_f32 v[246:247], v[110:111], v[246:247]
	v_pk_mul_f32 v[248:249], v[112:113], v[248:249]
	v_cvt_pk_bf16_f32 v174, v246, v247
	v_cvt_pk_bf16_f32 v175, v248, v249
	v_lshlrev_b32_e32 v246, 16, v176
	v_and_b32_e32 v247, 0xffff0000, v176
	v_lshlrev_b32_e32 v248, 16, v177
	v_and_b32_e32 v249, 0xffff0000, v177
	v_pk_mul_f32 v[246:247], v[106:107], v[246:247]
	v_pk_mul_f32 v[248:249], v[108:109], v[248:249]
	v_cvt_pk_bf16_f32 v176, v246, v247
	v_cvt_pk_bf16_f32 v177, v248, v249
	s_nop 1
	v_permlane16_swap_b32_e32 v174, v176
	v_permlane16_swap_b32_e32 v175, v177
	global_store_dwordx4 v[154:155], v[174:177], off offset:0
	s_nop 0
	s_mov_b32 s42, 0xa0000
	v_lshl_add_u64 v[148:149], v[144:145], 0, s[42:43]
	global_load_dwordx4 v[174:177], v[148:149], off offset:0
	s_mov_b32 s42, 0x50000
	v_lshl_add_u64 v[154:155], v[146:147], 0, s[42:43]
	s_waitcnt vmcnt(10)
	v_permlane16_swap_b32_e32 v178, v180
	v_permlane16_swap_b32_e32 v179, v181
	v_lshlrev_b32_e32 v246, 16, v178
	v_and_b32_e32 v247, 0xffff0000, v178
	v_lshlrev_b32_e32 v248, 16, v179
	v_and_b32_e32 v249, 0xffff0000, v179
	v_pk_mul_f32 v[246:247], v[102:103], v[246:247]
	v_pk_mul_f32 v[248:249], v[104:105], v[248:249]
	v_cvt_pk_bf16_f32 v178, v246, v247
	v_cvt_pk_bf16_f32 v179, v248, v249
	v_lshlrev_b32_e32 v246, 16, v180
	v_and_b32_e32 v247, 0xffff0000, v180
	v_lshlrev_b32_e32 v248, 16, v181
	v_and_b32_e32 v249, 0xffff0000, v181
	v_pk_mul_f32 v[246:247], v[98:99], v[246:247]
	v_pk_mul_f32 v[248:249], v[100:101], v[248:249]
	v_cvt_pk_bf16_f32 v180, v246, v247
	v_cvt_pk_bf16_f32 v181, v248, v249
	s_nop 1
	v_permlane16_swap_b32_e32 v178, v180
	v_permlane16_swap_b32_e32 v179, v181
	global_store_dwordx4 v[156:157], v[178:181], off offset:0
	s_nop 0
	s_mov_b32 s42, 0xb0000
	v_lshl_add_u64 v[148:149], v[144:145], 0, s[42:43]
	global_load_dwordx4 v[178:181], v[148:149], off offset:0
	s_mov_b32 s42, 0x58000
	v_lshl_add_u64 v[156:157], v[146:147], 0, s[42:43]
	s_waitcnt vmcnt(11)
	v_permlane16_swap_b32_e32 v182, v184
	v_permlane16_swap_b32_e32 v183, v185
	v_lshlrev_b32_e32 v246, 16, v182
	v_and_b32_e32 v247, 0xffff0000, v182
	v_lshlrev_b32_e32 v248, 16, v183
	v_and_b32_e32 v249, 0xffff0000, v183
	v_pk_mul_f32 v[246:247], v[94:95], v[246:247]
	v_pk_mul_f32 v[248:249], v[96:97], v[248:249]
	v_cvt_pk_bf16_f32 v182, v246, v247
	v_cvt_pk_bf16_f32 v183, v248, v249
	v_lshlrev_b32_e32 v246, 16, v184
	v_and_b32_e32 v247, 0xffff0000, v184
	v_lshlrev_b32_e32 v248, 16, v185
	v_and_b32_e32 v249, 0xffff0000, v185
	v_pk_mul_f32 v[246:247], v[90:91], v[246:247]
	v_pk_mul_f32 v[248:249], v[92:93], v[248:249]
	v_cvt_pk_bf16_f32 v184, v246, v247
	v_cvt_pk_bf16_f32 v185, v248, v249
	s_nop 1
	v_permlane16_swap_b32_e32 v182, v184
	v_permlane16_swap_b32_e32 v183, v185
	global_store_dwordx4 v[158:159], v[182:185], off offset:256
	s_nop 0
	s_mov_b32 s42, 0x80000
	v_lshl_add_u64 v[148:149], v[144:145], 0, s[42:43]
	global_load_dwordx4 v[182:185], v[148:149], off offset:256
	s_mov_b32 s42, 0x40000
	v_lshl_add_u64 v[158:159], v[146:147], 0, s[42:43]
	s_waitcnt vmcnt(12)
	v_permlane16_swap_b32_e32 v186, v188
	v_permlane16_swap_b32_e32 v187, v189
	v_lshlrev_b32_e32 v246, 16, v186
	v_and_b32_e32 v247, 0xffff0000, v186
	v_lshlrev_b32_e32 v248, 16, v187
	v_and_b32_e32 v249, 0xffff0000, v187
	v_pk_mul_f32 v[246:247], v[86:87], v[246:247]
	v_pk_mul_f32 v[248:249], v[88:89], v[248:249]
	v_cvt_pk_bf16_f32 v186, v246, v247
	v_cvt_pk_bf16_f32 v187, v248, v249
	v_lshlrev_b32_e32 v246, 16, v188
	v_and_b32_e32 v247, 0xffff0000, v188
	v_lshlrev_b32_e32 v248, 16, v189
	v_and_b32_e32 v249, 0xffff0000, v189
	v_pk_mul_f32 v[246:247], v[82:83], v[246:247]
	v_pk_mul_f32 v[248:249], v[84:85], v[248:249]
	v_cvt_pk_bf16_f32 v188, v246, v247
	v_cvt_pk_bf16_f32 v189, v248, v249
	s_nop 1
	v_permlane16_swap_b32_e32 v186, v188
	v_permlane16_swap_b32_e32 v187, v189
	global_store_dwordx4 v[160:161], v[186:189], off offset:256
	s_nop 0
	s_mov_b32 s42, 0x90000
	v_lshl_add_u64 v[148:149], v[144:145], 0, s[42:43]
	global_load_dwordx4 v[186:189], v[148:149], off offset:256
	s_mov_b32 s42, 0x48000
	v_lshl_add_u64 v[160:161], v[146:147], 0, s[42:43]
	s_waitcnt vmcnt(13)
	v_permlane16_swap_b32_e32 v190, v192
	v_permlane16_swap_b32_e32 v191, v193
	v_lshlrev_b32_e32 v246, 16, v190
	v_and_b32_e32 v247, 0xffff0000, v190
	v_lshlrev_b32_e32 v248, 16, v191
	v_and_b32_e32 v249, 0xffff0000, v191
	v_pk_mul_f32 v[246:247], v[78:79], v[246:247]
	v_pk_mul_f32 v[248:249], v[80:81], v[248:249]
	v_cvt_pk_bf16_f32 v190, v246, v247
	v_cvt_pk_bf16_f32 v191, v248, v249
	v_lshlrev_b32_e32 v246, 16, v192
	v_and_b32_e32 v247, 0xffff0000, v192
	v_lshlrev_b32_e32 v248, 16, v193
	v_and_b32_e32 v249, 0xffff0000, v193
	v_pk_mul_f32 v[246:247], v[74:75], v[246:247]
	v_pk_mul_f32 v[248:249], v[76:77], v[248:249]
	v_cvt_pk_bf16_f32 v192, v246, v247
	v_cvt_pk_bf16_f32 v193, v248, v249
	s_nop 1
	v_permlane16_swap_b32_e32 v190, v192
	v_permlane16_swap_b32_e32 v191, v193
	global_store_dwordx4 v[162:163], v[190:193], off offset:256
	s_nop 0
	s_mov_b32 s42, 0xa0000
	v_lshl_add_u64 v[148:149], v[144:145], 0, s[42:43]
	global_load_dwordx4 v[190:193], v[148:149], off offset:256
	s_mov_b32 s42, 0x50000
	v_lshl_add_u64 v[162:163], v[146:147], 0, s[42:43]
	s_waitcnt vmcnt(14)
	v_permlane16_swap_b32_e32 v194, v196
	v_permlane16_swap_b32_e32 v195, v197
	v_lshlrev_b32_e32 v246, 16, v194
	v_and_b32_e32 v247, 0xffff0000, v194
	v_lshlrev_b32_e32 v248, 16, v195
	v_and_b32_e32 v249, 0xffff0000, v195
	v_pk_mul_f32 v[246:247], v[70:71], v[246:247]
	v_pk_mul_f32 v[248:249], v[72:73], v[248:249]
	v_cvt_pk_bf16_f32 v194, v246, v247
	v_cvt_pk_bf16_f32 v195, v248, v249
	v_lshlrev_b32_e32 v246, 16, v196
	v_and_b32_e32 v247, 0xffff0000, v196
	v_lshlrev_b32_e32 v248, 16, v197
	v_and_b32_e32 v249, 0xffff0000, v197
	v_pk_mul_f32 v[246:247], v[66:67], v[246:247]
	v_pk_mul_f32 v[248:249], v[68:69], v[248:249]
	v_cvt_pk_bf16_f32 v196, v246, v247
	v_cvt_pk_bf16_f32 v197, v248, v249
	s_nop 1
	v_permlane16_swap_b32_e32 v194, v196
	v_permlane16_swap_b32_e32 v195, v197
	global_store_dwordx4 v[164:165], v[194:197], off offset:256
	s_nop 0
	s_mov_b32 s42, 0xb0000
	v_lshl_add_u64 v[148:149], v[144:145], 0, s[42:43]
	global_load_dwordx4 v[194:197], v[148:149], off offset:256
	s_mov_b32 s42, 0x58000
	v_lshl_add_u64 v[164:165], v[146:147], 0, s[42:43]
	s_waitcnt vmcnt(14)
	v_permlane16_swap_b32_e32 v166, v168
	v_permlane16_swap_b32_e32 v167, v169
	v_lshlrev_b32_e32 v246, 16, v166
	v_and_b32_e32 v247, 0xffff0000, v166
	v_lshlrev_b32_e32 v248, 16, v167
	v_and_b32_e32 v249, 0xffff0000, v167
	v_pk_mul_f32 v[246:247], v[62:63], v[246:247]
	v_pk_mul_f32 v[248:249], v[64:65], v[248:249]
	v_cvt_pk_bf16_f32 v166, v246, v247
	v_cvt_pk_bf16_f32 v167, v248, v249
	v_lshlrev_b32_e32 v246, 16, v168
	v_and_b32_e32 v247, 0xffff0000, v168
	v_lshlrev_b32_e32 v248, 16, v169
	v_and_b32_e32 v249, 0xffff0000, v169
	v_pk_mul_f32 v[246:247], v[58:59], v[246:247]
	v_pk_mul_f32 v[248:249], v[60:61], v[248:249]
	v_cvt_pk_bf16_f32 v168, v246, v247
	v_cvt_pk_bf16_f32 v169, v248, v249
	s_nop 1
	v_permlane16_swap_b32_e32 v166, v168
	v_permlane16_swap_b32_e32 v167, v169
	global_store_dwordx4 v[150:151], v[166:169], off offset:0
	s_waitcnt vmcnt(13)
	v_permlane16_swap_b32_e32 v170, v172
	v_permlane16_swap_b32_e32 v171, v173
	v_lshlrev_b32_e32 v246, 16, v170
	v_and_b32_e32 v247, 0xffff0000, v170
	v_lshlrev_b32_e32 v248, 16, v171
	v_and_b32_e32 v249, 0xffff0000, v171
	v_pk_mul_f32 v[246:247], v[54:55], v[246:247]
	v_pk_mul_f32 v[248:249], v[56:57], v[248:249]
	v_cvt_pk_bf16_f32 v170, v246, v247
	v_cvt_pk_bf16_f32 v171, v248, v249
	v_lshlrev_b32_e32 v246, 16, v172
	v_and_b32_e32 v247, 0xffff0000, v172
	v_lshlrev_b32_e32 v248, 16, v173
	v_and_b32_e32 v249, 0xffff0000, v173
	v_pk_mul_f32 v[246:247], v[50:51], v[246:247]
	v_pk_mul_f32 v[248:249], v[52:53], v[248:249]
	v_cvt_pk_bf16_f32 v172, v246, v247
	v_cvt_pk_bf16_f32 v173, v248, v249
	s_nop 1
	v_permlane16_swap_b32_e32 v170, v172
	v_permlane16_swap_b32_e32 v171, v173
	global_store_dwordx4 v[152:153], v[170:173], off offset:0
	s_waitcnt vmcnt(12)
	v_permlane16_swap_b32_e32 v174, v176
	v_permlane16_swap_b32_e32 v175, v177
	v_lshlrev_b32_e32 v246, 16, v174
	v_and_b32_e32 v247, 0xffff0000, v174
	v_lshlrev_b32_e32 v248, 16, v175
	v_and_b32_e32 v249, 0xffff0000, v175
	v_pk_mul_f32 v[246:247], v[46:47], v[246:247]
	v_pk_mul_f32 v[248:249], v[48:49], v[248:249]
	v_cvt_pk_bf16_f32 v174, v246, v247
	v_cvt_pk_bf16_f32 v175, v248, v249
	v_lshlrev_b32_e32 v246, 16, v176
	v_and_b32_e32 v247, 0xffff0000, v176
	v_lshlrev_b32_e32 v248, 16, v177
	v_and_b32_e32 v249, 0xffff0000, v177
	v_pk_mul_f32 v[246:247], v[42:43], v[246:247]
	v_pk_mul_f32 v[248:249], v[44:45], v[248:249]
	v_cvt_pk_bf16_f32 v176, v246, v247
	v_cvt_pk_bf16_f32 v177, v248, v249
	s_nop 1
	v_permlane16_swap_b32_e32 v174, v176
	v_permlane16_swap_b32_e32 v175, v177
	global_store_dwordx4 v[154:155], v[174:177], off offset:0
	s_waitcnt vmcnt(11)
	v_permlane16_swap_b32_e32 v178, v180
	v_permlane16_swap_b32_e32 v179, v181
	v_lshlrev_b32_e32 v246, 16, v178
	v_and_b32_e32 v247, 0xffff0000, v178
	v_lshlrev_b32_e32 v248, 16, v179
	v_and_b32_e32 v249, 0xffff0000, v179
	v_pk_mul_f32 v[246:247], v[38:39], v[246:247]
	v_pk_mul_f32 v[248:249], v[40:41], v[248:249]
	v_cvt_pk_bf16_f32 v178, v246, v247
	v_cvt_pk_bf16_f32 v179, v248, v249
	v_lshlrev_b32_e32 v246, 16, v180
	v_and_b32_e32 v247, 0xffff0000, v180
	v_lshlrev_b32_e32 v248, 16, v181
	v_and_b32_e32 v249, 0xffff0000, v181
	v_pk_mul_f32 v[246:247], v[34:35], v[246:247]
	v_pk_mul_f32 v[248:249], v[36:37], v[248:249]
	v_cvt_pk_bf16_f32 v180, v246, v247
	v_cvt_pk_bf16_f32 v181, v248, v249
	s_nop 1
	v_permlane16_swap_b32_e32 v178, v180
	v_permlane16_swap_b32_e32 v179, v181
	global_store_dwordx4 v[156:157], v[178:181], off offset:0
	s_waitcnt vmcnt(10)
	v_permlane16_swap_b32_e32 v182, v184
	v_permlane16_swap_b32_e32 v183, v185
	v_lshlrev_b32_e32 v246, 16, v182
	v_and_b32_e32 v247, 0xffff0000, v182
	v_lshlrev_b32_e32 v248, 16, v183
	v_and_b32_e32 v249, 0xffff0000, v183
	v_pk_mul_f32 v[246:247], v[30:31], v[246:247]
	v_pk_mul_f32 v[248:249], v[32:33], v[248:249]
	v_cvt_pk_bf16_f32 v182, v246, v247
	v_cvt_pk_bf16_f32 v183, v248, v249
	v_lshlrev_b32_e32 v246, 16, v184
	v_and_b32_e32 v247, 0xffff0000, v184
	v_lshlrev_b32_e32 v248, 16, v185
	v_and_b32_e32 v249, 0xffff0000, v185
	v_pk_mul_f32 v[246:247], v[26:27], v[246:247]
	v_pk_mul_f32 v[248:249], v[28:29], v[248:249]
	v_cvt_pk_bf16_f32 v184, v246, v247
	v_cvt_pk_bf16_f32 v185, v248, v249
	s_nop 1
	v_permlane16_swap_b32_e32 v182, v184
	v_permlane16_swap_b32_e32 v183, v185
	global_store_dwordx4 v[158:159], v[182:185], off offset:256
	s_waitcnt vmcnt(9)
	v_permlane16_swap_b32_e32 v186, v188
	v_permlane16_swap_b32_e32 v187, v189
	v_lshlrev_b32_e32 v246, 16, v186
	v_and_b32_e32 v247, 0xffff0000, v186
	v_lshlrev_b32_e32 v248, 16, v187
	v_and_b32_e32 v249, 0xffff0000, v187
	v_pk_mul_f32 v[246:247], v[22:23], v[246:247]
	v_pk_mul_f32 v[248:249], v[24:25], v[248:249]
	v_cvt_pk_bf16_f32 v186, v246, v247
	v_cvt_pk_bf16_f32 v187, v248, v249
	v_lshlrev_b32_e32 v246, 16, v188
	v_and_b32_e32 v247, 0xffff0000, v188
	v_lshlrev_b32_e32 v248, 16, v189
	v_and_b32_e32 v249, 0xffff0000, v189
	v_pk_mul_f32 v[246:247], v[18:19], v[246:247]
	v_pk_mul_f32 v[248:249], v[20:21], v[248:249]
	v_cvt_pk_bf16_f32 v188, v246, v247
	v_cvt_pk_bf16_f32 v189, v248, v249
	s_nop 1
	v_permlane16_swap_b32_e32 v186, v188
	v_permlane16_swap_b32_e32 v187, v189
	global_store_dwordx4 v[160:161], v[186:189], off offset:256
	s_waitcnt vmcnt(8)
	v_permlane16_swap_b32_e32 v190, v192
	v_permlane16_swap_b32_e32 v191, v193
	v_lshlrev_b32_e32 v246, 16, v190
	v_and_b32_e32 v247, 0xffff0000, v190
	v_lshlrev_b32_e32 v248, 16, v191
	v_and_b32_e32 v249, 0xffff0000, v191
	v_pk_mul_f32 v[246:247], v[14:15], v[246:247]
	v_pk_mul_f32 v[248:249], v[16:17], v[248:249]
	v_cvt_pk_bf16_f32 v190, v246, v247
	v_cvt_pk_bf16_f32 v191, v248, v249
	v_lshlrev_b32_e32 v246, 16, v192
	v_and_b32_e32 v247, 0xffff0000, v192
	v_lshlrev_b32_e32 v248, 16, v193
	v_and_b32_e32 v249, 0xffff0000, v193
	v_pk_mul_f32 v[246:247], v[10:11], v[246:247]
	v_pk_mul_f32 v[248:249], v[12:13], v[248:249]
	v_cvt_pk_bf16_f32 v192, v246, v247
	v_cvt_pk_bf16_f32 v193, v248, v249
	s_nop 1
	v_permlane16_swap_b32_e32 v190, v192
	v_permlane16_swap_b32_e32 v191, v193
	global_store_dwordx4 v[162:163], v[190:193], off offset:256
	s_waitcnt vmcnt(7)
	v_permlane16_swap_b32_e32 v194, v196
	v_permlane16_swap_b32_e32 v195, v197
	v_lshlrev_b32_e32 v246, 16, v194
	v_and_b32_e32 v247, 0xffff0000, v194
	v_lshlrev_b32_e32 v248, 16, v195
	v_and_b32_e32 v249, 0xffff0000, v195
	v_pk_mul_f32 v[246:247], v[6:7], v[246:247]
	v_pk_mul_f32 v[248:249], v[8:9], v[248:249]
	v_cvt_pk_bf16_f32 v194, v246, v247
	v_cvt_pk_bf16_f32 v195, v248, v249
	v_lshlrev_b32_e32 v246, 16, v196
	v_and_b32_e32 v247, 0xffff0000, v196
	v_lshlrev_b32_e32 v248, 16, v197
	v_and_b32_e32 v249, 0xffff0000, v197
	v_pk_mul_f32 v[246:247], v[2:3], v[246:247]
	v_pk_mul_f32 v[248:249], v[4:5], v[248:249]
	v_cvt_pk_bf16_f32 v196, v246, v247
	v_cvt_pk_bf16_f32 v197, v248, v249
	s_nop 1
	v_permlane16_swap_b32_e32 v194, v196
	v_permlane16_swap_b32_e32 v195, v197
	global_store_dwordx4 v[164:165], v[194:197], off offset:256
	s_branch .Lmix_done
.Lmix_pass1:
	s_mov_b32 s42, 0x0
	v_lshl_add_u64 v[148:149], v[144:145], 0, s[42:43]
	global_load_dwordx4 v[166:169], v[148:149], off offset:0
	s_mov_b32 s42, 0x0
	v_lshl_add_u64 v[150:151], v[146:147], 0, s[42:43]
	global_load_dwordx4 v[198:201], v[150:151], off offset:0
	s_mov_b32 s42, 0x10000
	v_lshl_add_u64 v[148:149], v[144:145], 0, s[42:43]
	global_load_dwordx4 v[170:173], v[148:149], off offset:0
	s_mov_b32 s42, 0x8000
	v_lshl_add_u64 v[152:153], v[146:147], 0, s[42:43]
	global_load_dwordx4 v[202:205], v[152:153], off offset:0
	s_mov_b32 s42, 0x20000
	v_lshl_add_u64 v[148:149], v[144:145], 0, s[42:43]
	global_load_dwordx4 v[174:177], v[148:149], off offset:0
	s_mov_b32 s42, 0x10000
	v_lshl_add_u64 v[154:155], v[146:147], 0, s[42:43]
	global_load_dwordx4 v[206:209], v[154:155], off offset:0
	s_mov_b32 s42, 0x30000
	v_lshl_add_u64 v[148:149], v[144:145], 0, s[42:43]
	global_load_dwordx4 v[178:181], v[148:149], off offset:0
	s_mov_b32 s42, 0x18000
	v_lshl_add_u64 v[156:157], v[146:147], 0, s[42:43]
	global_load_dwordx4 v[226:229], v[156:157], off offset:0
	s_mov_b32 s42, 0x0
	v_lshl_add_u64 v[148:149], v[144:145], 0, s[42:43]
	global_load_dwordx4 v[182:185], v[148:149], off offset:256
	s_mov_b32 s42, 0x0
	v_lshl_add_u64 v[158:159], v[146:147], 0, s[42:43]
	global_load_dwordx4 v[230:233], v[158:159], off offset:256
	s_mov_b32 s42, 0x10000
	v_lshl_add_u64 v[148:149], v[144:145], 0, s[42:43]
	global_load_dwordx4 v[186:189], v[148:149], off offset:256
	s_mov_b32 s42, 0x8000
	v_lshl_add_u64 v[160:161], v[146:147], 0, s[42:43]
	global_load_dwordx4 v[234:237], v[160:161], off offset:256
	s_mov_b32 s42, 0x20000
	v_lshl_add_u64 v[148:149], v[144:145], 0, s[42:43]
	global_load_dwordx4 v[190:193], v[148:149], off offset:256
	s_mov_b32 s42, 0x10000
	v_lshl_add_u64 v[162:163], v[146:147], 0, s[42:43]
	global_load_dwordx4 v[238:241], v[162:163], off offset:256
	s_mov_b32 s42, 0x30000
	v_lshl_add_u64 v[148:149], v[144:145], 0, s[42:43]
	global_load_dwordx4 v[194:197], v[148:149], off offset:256
	s_mov_b32 s42, 0x18000
	v_lshl_add_u64 v[164:165], v[146:147], 0, s[42:43]
	global_load_dwordx4 v[242:245], v[164:165], off offset:256
	s_waitcnt vmcnt(14)
	v_permlane16_swap_b32_e32 v166, v168
	v_permlane16_swap_b32_e32 v167, v169
	v_permlane16_swap_b32_e32 v198, v200
	v_permlane16_swap_b32_e32 v199, v201
	v_lshlrev_b32_e32 v246, 16, v166
	v_and_b32_e32 v247, 0xffff0000, v166
	v_lshlrev_b32_e32 v248, 16, v167
	v_and_b32_e32 v249, 0xffff0000, v167
	v_pk_mul_f32 v[246:247], v[126:127], v[246:247]
	v_pk_mul_f32 v[248:249], v[128:129], v[248:249]
	v_lshlrev_b32_e32 v216, 16, v198
	v_and_b32_e32 v217, 0xffff0000, v198
	v_lshlrev_b32_e32 v220, 16, v199
	v_and_b32_e32 v221, 0xffff0000, v199
	v_pk_add_f32 v[246:247], v[246:247], v[216:217]
	v_pk_add_f32 v[248:249], v[248:249], v[220:221]
	v_cvt_pk_bf16_f32 v166, v246, v247
	v_cvt_pk_bf16_f32 v167, v248, v249
	v_lshlrev_b32_e32 v246, 16, v168
	v_and_b32_e32 v247, 0xffff0000, v168
	v_lshlrev_b32_e32 v248, 16, v169
	v_and_b32_e32 v249, 0xffff0000, v169
	v_pk_mul_f32 v[246:247], v[122:123], v[246:247]
	v_pk_mul_f32 v[248:249], v[124:125], v[248:249]
	v_lshlrev_b32_e32 v216, 16, v200
	v_and_b32_e32 v217, 0xffff0000, v200
	v_lshlrev_b32_e32 v220, 16, v201
	v_and_b32_e32 v221, 0xffff0000, v201
	v_pk_add_f32 v[246:247], v[246:247], v[216:217]
	v_pk_add_f32 v[248:249], v[248:249], v[220:221]
	v_cvt_pk_bf16_f32 v168, v246, v247
	v_cvt_pk_bf16_f32 v169, v248, v249
	s_nop 1
	v_permlane16_swap_b32_e32 v166, v168
	v_permlane16_swap_b32_e32 v167, v169
	global_store_dwordx4 v[150:151], v[166:169], off offset:0
	s_nop 0
	s_mov_b32 s42, 0x80000
	v_lshl_add_u64 v[148:149], v[144:145], 0, s[42:43]
	global_load_dwordx4 v[166:169], v[148:149], off offset:0
	s_mov_b32 s42, 0x40000
	v_lshl_add_u64 v[150:151], v[146:147], 0, s[42:43]
	global_load_dwordx4 v[198:201], v[150:151], off offset:0
	s_waitcnt vmcnt(15)
	v_permlane16_swap_b32_e32 v170, v172
	v_permlane16_swap_b32_e32 v171, v173
	v_permlane16_swap_b32_e32 v202, v204
	v_permlane16_swap_b32_e32 v203, v205
	v_lshlrev_b32_e32 v246, 16, v170
	v_and_b32_e32 v247, 0xffff0000, v170
	v_lshlrev_b32_e32 v248, 16, v171
	v_and_b32_e32 v249, 0xffff0000, v171
	v_pk_mul_f32 v[246:247], v[118:119], v[246:247]
	v_pk_mul_f32 v[248:249], v[120:121], v[248:249]
	v_lshlrev_b32_e32 v216, 16, v202
	v_and_b32_e32 v217, 0xffff0000, v202
	v_lshlrev_b32_e32 v220, 16, v203
	v_and_b32_e32 v221, 0xffff0000, v203
	v_pk_add_f32 v[246:247], v[246:247], v[216:217]
	v_pk_add_f32 v[248:249], v[248:249], v[220:221]
	v_cvt_pk_bf16_f32 v170, v246, v247
	v_cvt_pk_bf16_f32 v171, v248, v249
	v_lshlrev_b32_e32 v246, 16, v172
	v_and_b32_e32 v247, 0xffff0000, v172
	v_lshlrev_b32_e32 v248, 16, v173
	v_and_b32_e32 v249, 0xffff0000, v173
	v_pk_mul_f32 v[246:247], v[114:115], v[246:247]
	v_pk_mul_f32 v[248:249], v[116:117], v[248:249]
	v_lshlrev_b32_e32 v216, 16, v204
	v_and_b32_e32 v217, 0xffff0000, v204
	v_lshlrev_b32_e32 v220, 16, v205
	v_and_b32_e32 v221, 0xffff0000, v205
	v_pk_add_f32 v[246:247], v[246:247], v[216:217]
	v_pk_add_f32 v[248:249], v[248:249], v[220:221]
	v_cvt_pk_bf16_f32 v172, v246, v247
	v_cvt_pk_bf16_f32 v173, v248, v249
	s_nop 1
	v_permlane16_swap_b32_e32 v170, v172
	v_permlane16_swap_b32_e32 v171, v173
	global_store_dwordx4 v[152:153], v[170:173], off offset:0
	s_nop 0
	s_mov_b32 s42, 0x90000
	v_lshl_add_u64 v[148:149], v[144:145], 0, s[42:43]
	global_load_dwordx4 v[170:173], v[148:149], off offset:0
	s_mov_b32 s42, 0x48000
	v_lshl_add_u64 v[152:153], v[146:147], 0, s[42:43]
	global_load_dwordx4 v[202:205], v[152:153], off offset:0
	s_waitcnt vmcnt(16)
	v_permlane16_swap_b32_e32 v174, v176
	v_permlane16_swap_b32_e32 v175, v177
	v_permlane16_swap_b32_e32 v206, v208
	v_permlane16_swap_b32_e32 v207, v209
	v_lshlrev_b32_e32 v246, 16, v174
	v_and_b32_e32 v247, 0xffff0000, v174
	v_lshlrev_b32_e32 v248, 16, v175
	v_and_b32_e32 v249, 0xffff0000, v175
	v_pk_mul_f32 v[246:247], v[110:111], v[246:247]
	v_pk_mul_f32 v[248:249], v[112:113], v[248:249]
	v_lshlrev_b32_e32 v216, 16, v206
	v_and_b32_e32 v217, 0xffff0000, v206
	v_lshlrev_b32_e32 v220, 16, v207
	v_and_b32_e32 v221, 0xffff0000, v207
	v_pk_add_f32 v[246:247], v[246:247], v[216:217]
	v_pk_add_f32 v[248:249], v[248:249], v[220:221]
	v_cvt_pk_bf16_f32 v174, v246, v247
	v_cvt_pk_bf16_f32 v175, v248, v249
	v_lshlrev_b32_e32 v246, 16, v176
	v_and_b32_e32 v247, 0xffff0000, v176
	v_lshlrev_b32_e32 v248, 16, v177
	v_and_b32_e32 v249, 0xffff0000, v177
	v_pk_mul_f32 v[246:247], v[106:107], v[246:247]
	v_pk_mul_f32 v[248:249], v[108:109], v[248:249]
	v_lshlrev_b32_e32 v216, 16, v208
	v_and_b32_e32 v217, 0xffff0000, v208
	v_lshlrev_b32_e32 v220, 16, v209
	v_and_b32_e32 v221, 0xffff0000, v209
	v_pk_add_f32 v[246:247], v[246:247], v[216:217]
	v_pk_add_f32 v[248:249], v[248:249], v[220:221]
	v_cvt_pk_bf16_f32 v176, v246, v247
	v_cvt_pk_bf16_f32 v177, v248, v249
	s_nop 1
	v_permlane16_swap_b32_e32 v174, v176
	v_permlane16_swap_b32_e32 v175, v177
	global_store_dwordx4 v[154:155], v[174:177], off offset:0
	s_nop 0
	s_mov_b32 s42, 0xa0000
	v_lshl_add_u64 v[148:149], v[144:145], 0, s[42:43]
	global_load_dwordx4 v[174:177], v[148:149], off offset:0
	s_mov_b32 s42, 0x50000
	v_lshl_add_u64 v[154:155], v[146:147], 0, s[42:43]
	global_load_dwordx4 v[206:209], v[154:155], off offset:0
	s_waitcnt vmcnt(17)
	v_permlane16_swap_b32_e32 v178, v180
	v_permlane16_swap_b32_e32 v179, v181
	v_permlane16_swap_b32_e32 v226, v228
	v_permlane16_swap_b32_e32 v227, v229
	v_lshlrev_b32_e32 v246, 16, v178
	v_and_b32_e32 v247, 0xffff0000, v178
	v_lshlrev_b32_e32 v248, 16, v179
	v_and_b32_e32 v249, 0xffff0000, v179
	v_pk_mul_f32 v[246:247], v[102:103], v[246:247]
	v_pk_mul_f32 v[248:249], v[104:105], v[248:249]
	v_lshlrev_b32_e32 v216, 16, v226
	v_and_b32_e32 v217, 0xffff0000, v226
	v_lshlrev_b32_e32 v220, 16, v227
	v_and_b32_e32 v221, 0xffff0000, v227
	v_pk_add_f32 v[246:247], v[246:247], v[216:217]
	v_pk_add_f32 v[248:249], v[248:249], v[220:221]
	v_cvt_pk_bf16_f32 v178, v246, v247
	v_cvt_pk_bf16_f32 v179, v248, v249
	v_lshlrev_b32_e32 v246, 16, v180
	v_and_b32_e32 v247, 0xffff0000, v180
	v_lshlrev_b32_e32 v248, 16, v181
	v_and_b32_e32 v249, 0xffff0000, v181
	v_pk_mul_f32 v[246:247], v[98:99], v[246:247]
	v_pk_mul_f32 v[248:249], v[100:101], v[248:249]
	v_lshlrev_b32_e32 v216, 16, v228
	v_and_b32_e32 v217, 0xffff0000, v228
	v_lshlrev_b32_e32 v220, 16, v229
	v_and_b32_e32 v221, 0xffff0000, v229
	v_pk_add_f32 v[246:247], v[246:247], v[216:217]
	v_pk_add_f32 v[248:249], v[248:249], v[220:221]
	v_cvt_pk_bf16_f32 v180, v246, v247
	v_cvt_pk_bf16_f32 v181, v248, v249
	s_nop 1
	v_permlane16_swap_b32_e32 v178, v180
	v_permlane16_swap_b32_e32 v179, v181
	global_store_dwordx4 v[156:157], v[178:181], off offset:0
	s_nop 0
	s_mov_b32 s42, 0xb0000
	v_lshl_add_u64 v[148:149], v[144:145], 0, s[42:43]
	global_load_dwordx4 v[178:181], v[148:149], off offset:0
	s_mov_b32 s42, 0x58000
	v_lshl_add_u64 v[156:157], v[146:147], 0, s[42:43]
	global_load_dwordx4 v[226:229], v[156:157], off offset:0
	s_waitcnt vmcnt(18)
	v_permlane16_swap_b32_e32 v182, v184
	v_permlane16_swap_b32_e32 v183, v185
	v_permlane16_swap_b32_e32 v230, v232
	v_permlane16_swap_b32_e32 v231, v233
	v_lshlrev_b32_e32 v246, 16, v182
	v_and_b32_e32 v247, 0xffff0000, v182
	v_lshlrev_b32_e32 v248, 16, v183
	v_and_b32_e32 v249, 0xffff0000, v183
	v_pk_mul_f32 v[246:247], v[94:95], v[246:247]
	v_pk_mul_f32 v[248:249], v[96:97], v[248:249]
	v_lshlrev_b32_e32 v216, 16, v230
	v_and_b32_e32 v217, 0xffff0000, v230
	v_lshlrev_b32_e32 v220, 16, v231
	v_and_b32_e32 v221, 0xffff0000, v231
	v_pk_add_f32 v[246:247], v[246:247], v[216:217]
	v_pk_add_f32 v[248:249], v[248:249], v[220:221]
	v_cvt_pk_bf16_f32 v182, v246, v247
	v_cvt_pk_bf16_f32 v183, v248, v249
	v_lshlrev_b32_e32 v246, 16, v184
	v_and_b32_e32 v247, 0xffff0000, v184
	v_lshlrev_b32_e32 v248, 16, v185
	v_and_b32_e32 v249, 0xffff0000, v185
	v_pk_mul_f32 v[246:247], v[90:91], v[246:247]
	v_pk_mul_f32 v[248:249], v[92:93], v[248:249]
	v_lshlrev_b32_e32 v216, 16, v232
	v_and_b32_e32 v217, 0xffff0000, v232
	v_lshlrev_b32_e32 v220, 16, v233
	v_and_b32_e32 v221, 0xffff0000, v233
	v_pk_add_f32 v[246:247], v[246:247], v[216:217]
	v_pk_add_f32 v[248:249], v[248:249], v[220:221]
	v_cvt_pk_bf16_f32 v184, v246, v247
	v_cvt_pk_bf16_f32 v185, v248, v249
	s_nop 1
	v_permlane16_swap_b32_e32 v182, v184
	v_permlane16_swap_b32_e32 v183, v185
	global_store_dwordx4 v[158:159], v[182:185], off offset:256
	s_nop 0
	s_mov_b32 s42, 0x80000
	v_lshl_add_u64 v[148:149], v[144:145], 0, s[42:43]
	global_load_dwordx4 v[182:185], v[148:149], off offset:256
	s_mov_b32 s42, 0x40000
	v_lshl_add_u64 v[158:159], v[146:147], 0, s[42:43]
	global_load_dwordx4 v[230:233], v[158:159], off offset:256
	s_waitcnt vmcnt(19)
	v_permlane16_swap_b32_e32 v186, v188
	v_permlane16_swap_b32_e32 v187, v189
	v_permlane16_swap_b32_e32 v234, v236
	v_permlane16_swap_b32_e32 v235, v237
	v_lshlrev_b32_e32 v246, 16, v186
	v_and_b32_e32 v247, 0xffff0000, v186
	v_lshlrev_b32_e32 v248, 16, v187
	v_and_b32_e32 v249, 0xffff0000, v187
	v_pk_mul_f32 v[246:247], v[86:87], v[246:247]
	v_pk_mul_f32 v[248:249], v[88:89], v[248:249]
	v_lshlrev_b32_e32 v216, 16, v234
	v_and_b32_e32 v217, 0xffff0000, v234
	v_lshlrev_b32_e32 v220, 16, v235
	v_and_b32_e32 v221, 0xffff0000, v235
	v_pk_add_f32 v[246:247], v[246:247], v[216:217]
	v_pk_add_f32 v[248:249], v[248:249], v[220:221]
	v_cvt_pk_bf16_f32 v186, v246, v247
	v_cvt_pk_bf16_f32 v187, v248, v249
	v_lshlrev_b32_e32 v246, 16, v188
	v_and_b32_e32 v247, 0xffff0000, v188
	v_lshlrev_b32_e32 v248, 16, v189
	v_and_b32_e32 v249, 0xffff0000, v189
	v_pk_mul_f32 v[246:247], v[82:83], v[246:247]
	v_pk_mul_f32 v[248:249], v[84:85], v[248:249]
	v_lshlrev_b32_e32 v216, 16, v236
	v_and_b32_e32 v217, 0xffff0000, v236
	v_lshlrev_b32_e32 v220, 16, v237
	v_and_b32_e32 v221, 0xffff0000, v237
	v_pk_add_f32 v[246:247], v[246:247], v[216:217]
	v_pk_add_f32 v[248:249], v[248:249], v[220:221]
	v_cvt_pk_bf16_f32 v188, v246, v247
	v_cvt_pk_bf16_f32 v189, v248, v249
	s_nop 1
	v_permlane16_swap_b32_e32 v186, v188
	v_permlane16_swap_b32_e32 v187, v189
	global_store_dwordx4 v[160:161], v[186:189], off offset:256
	s_nop 0
	s_mov_b32 s42, 0x90000
	v_lshl_add_u64 v[148:149], v[144:145], 0, s[42:43]
	global_load_dwordx4 v[186:189], v[148:149], off offset:256
	s_mov_b32 s42, 0x48000
	v_lshl_add_u64 v[160:161], v[146:147], 0, s[42:43]
	global_load_dwordx4 v[234:237], v[160:161], off offset:256
	s_waitcnt vmcnt(20)
	v_permlane16_swap_b32_e32 v190, v192
	v_permlane16_swap_b32_e32 v191, v193
	v_permlane16_swap_b32_e32 v238, v240
	v_permlane16_swap_b32_e32 v239, v241
	v_lshlrev_b32_e32 v246, 16, v190
	v_and_b32_e32 v247, 0xffff0000, v190
	v_lshlrev_b32_e32 v248, 16, v191
	v_and_b32_e32 v249, 0xffff0000, v191
	v_pk_mul_f32 v[246:247], v[78:79], v[246:247]
	v_pk_mul_f32 v[248:249], v[80:81], v[248:249]
	v_lshlrev_b32_e32 v216, 16, v238
	v_and_b32_e32 v217, 0xffff0000, v238
	v_lshlrev_b32_e32 v220, 16, v239
	v_and_b32_e32 v221, 0xffff0000, v239
	v_pk_add_f32 v[246:247], v[246:247], v[216:217]
	v_pk_add_f32 v[248:249], v[248:249], v[220:221]
	v_cvt_pk_bf16_f32 v190, v246, v247
	v_cvt_pk_bf16_f32 v191, v248, v249
	v_lshlrev_b32_e32 v246, 16, v192
	v_and_b32_e32 v247, 0xffff0000, v192
	v_lshlrev_b32_e32 v248, 16, v193
	v_and_b32_e32 v249, 0xffff0000, v193
	v_pk_mul_f32 v[246:247], v[74:75], v[246:247]
	v_pk_mul_f32 v[248:249], v[76:77], v[248:249]
	v_lshlrev_b32_e32 v216, 16, v240
	v_and_b32_e32 v217, 0xffff0000, v240
	v_lshlrev_b32_e32 v220, 16, v241
	v_and_b32_e32 v221, 0xffff0000, v241
	v_pk_add_f32 v[246:247], v[246:247], v[216:217]
	v_pk_add_f32 v[248:249], v[248:249], v[220:221]
	v_cvt_pk_bf16_f32 v192, v246, v247
	v_cvt_pk_bf16_f32 v193, v248, v249
	s_nop 1
	v_permlane16_swap_b32_e32 v190, v192
	v_permlane16_swap_b32_e32 v191, v193
	global_store_dwordx4 v[162:163], v[190:193], off offset:256
	s_nop 0
	s_mov_b32 s42, 0xa0000
	v_lshl_add_u64 v[148:149], v[144:145], 0, s[42:43]
	global_load_dwordx4 v[190:193], v[148:149], off offset:256
	s_mov_b32 s42, 0x50000
	v_lshl_add_u64 v[162:163], v[146:147], 0, s[42:43]
	global_load_dwordx4 v[238:241], v[162:163], off offset:256
	s_waitcnt vmcnt(21)
	v_permlane16_swap_b32_e32 v194, v196
	v_permlane16_swap_b32_e32 v195, v197
	v_permlane16_swap_b32_e32 v242, v244
	v_permlane16_swap_b32_e32 v243, v245
	v_lshlrev_b32_e32 v246, 16, v194
	v_and_b32_e32 v247, 0xffff0000, v194
	v_lshlrev_b32_e32 v248, 16, v195
	v_and_b32_e32 v249, 0xffff0000, v195
	v_pk_mul_f32 v[246:247], v[70:71], v[246:247]
	v_pk_mul_f32 v[248:249], v[72:73], v[248:249]
	v_lshlrev_b32_e32 v216, 16, v242
	v_and_b32_e32 v217, 0xffff0000, v242
	v_lshlrev_b32_e32 v220, 16, v243
	v_and_b32_e32 v221, 0xffff0000, v243
	v_pk_add_f32 v[246:247], v[246:247], v[216:217]
	v_pk_add_f32 v[248:249], v[248:249], v[220:221]
	v_cvt_pk_bf16_f32 v194, v246, v247
	v_cvt_pk_bf16_f32 v195, v248, v249
	v_lshlrev_b32_e32 v246, 16, v196
	v_and_b32_e32 v247, 0xffff0000, v196
	v_lshlrev_b32_e32 v248, 16, v197
	v_and_b32_e32 v249, 0xffff0000, v197
	v_pk_mul_f32 v[246:247], v[66:67], v[246:247]
	v_pk_mul_f32 v[248:249], v[68:69], v[248:249]
	v_lshlrev_b32_e32 v216, 16, v244
	v_and_b32_e32 v217, 0xffff0000, v244
	v_lshlrev_b32_e32 v220, 16, v245
	v_and_b32_e32 v221, 0xffff0000, v245
	v_pk_add_f32 v[246:247], v[246:247], v[216:217]
	v_pk_add_f32 v[248:249], v[248:249], v[220:221]
	v_cvt_pk_bf16_f32 v196, v246, v247
	v_cvt_pk_bf16_f32 v197, v248, v249
	s_nop 1
	v_permlane16_swap_b32_e32 v194, v196
	v_permlane16_swap_b32_e32 v195, v197
	global_store_dwordx4 v[164:165], v[194:197], off offset:256
	s_nop 0
	s_mov_b32 s42, 0xb0000
	v_lshl_add_u64 v[148:149], v[144:145], 0, s[42:43]
	global_load_dwordx4 v[194:197], v[148:149], off offset:256
	s_mov_b32 s42, 0x58000
	v_lshl_add_u64 v[164:165], v[146:147], 0, s[42:43]
	global_load_dwordx4 v[242:245], v[164:165], off offset:256
	s_waitcnt vmcnt(21)
	v_permlane16_swap_b32_e32 v166, v168
	v_permlane16_swap_b32_e32 v167, v169
	v_permlane16_swap_b32_e32 v198, v200
	v_permlane16_swap_b32_e32 v199, v201
	v_lshlrev_b32_e32 v246, 16, v166
	v_and_b32_e32 v247, 0xffff0000, v166
	v_lshlrev_b32_e32 v248, 16, v167
	v_and_b32_e32 v249, 0xffff0000, v167
	v_pk_mul_f32 v[246:247], v[62:63], v[246:247]
	v_pk_mul_f32 v[248:249], v[64:65], v[248:249]
	v_lshlrev_b32_e32 v216, 16, v198
	v_and_b32_e32 v217, 0xffff0000, v198
	v_lshlrev_b32_e32 v220, 16, v199
	v_and_b32_e32 v221, 0xffff0000, v199
	v_pk_add_f32 v[246:247], v[246:247], v[216:217]
	v_pk_add_f32 v[248:249], v[248:249], v[220:221]
	v_cvt_pk_bf16_f32 v166, v246, v247
	v_cvt_pk_bf16_f32 v167, v248, v249
	v_lshlrev_b32_e32 v246, 16, v168
	v_and_b32_e32 v247, 0xffff0000, v168
	v_lshlrev_b32_e32 v248, 16, v169
	v_and_b32_e32 v249, 0xffff0000, v169
	v_pk_mul_f32 v[246:247], v[58:59], v[246:247]
	v_pk_mul_f32 v[248:249], v[60:61], v[248:249]
	v_lshlrev_b32_e32 v216, 16, v200
	v_and_b32_e32 v217, 0xffff0000, v200
	v_lshlrev_b32_e32 v220, 16, v201
	v_and_b32_e32 v221, 0xffff0000, v201
	v_pk_add_f32 v[246:247], v[246:247], v[216:217]
	v_pk_add_f32 v[248:249], v[248:249], v[220:221]
	v_cvt_pk_bf16_f32 v168, v246, v247
	v_cvt_pk_bf16_f32 v169, v248, v249
	s_nop 1
	v_permlane16_swap_b32_e32 v166, v168
	v_permlane16_swap_b32_e32 v167, v169
	global_store_dwordx4 v[150:151], v[166:169], off offset:0
	s_waitcnt vmcnt(19)
	v_permlane16_swap_b32_e32 v170, v172
	v_permlane16_swap_b32_e32 v171, v173
	v_permlane16_swap_b32_e32 v202, v204
	v_permlane16_swap_b32_e32 v203, v205
	v_lshlrev_b32_e32 v246, 16, v170
	v_and_b32_e32 v247, 0xffff0000, v170
	v_lshlrev_b32_e32 v248, 16, v171
	v_and_b32_e32 v249, 0xffff0000, v171
	v_pk_mul_f32 v[246:247], v[54:55], v[246:247]
	v_pk_mul_f32 v[248:249], v[56:57], v[248:249]
	v_lshlrev_b32_e32 v216, 16, v202
	v_and_b32_e32 v217, 0xffff0000, v202
	v_lshlrev_b32_e32 v220, 16, v203
	v_and_b32_e32 v221, 0xffff0000, v203
	v_pk_add_f32 v[246:247], v[246:247], v[216:217]
	v_pk_add_f32 v[248:249], v[248:249], v[220:221]
	v_cvt_pk_bf16_f32 v170, v246, v247
	v_cvt_pk_bf16_f32 v171, v248, v249
	v_lshlrev_b32_e32 v246, 16, v172
	v_and_b32_e32 v247, 0xffff0000, v172
	v_lshlrev_b32_e32 v248, 16, v173
	v_and_b32_e32 v249, 0xffff0000, v173
	v_pk_mul_f32 v[246:247], v[50:51], v[246:247]
	v_pk_mul_f32 v[248:249], v[52:53], v[248:249]
	v_lshlrev_b32_e32 v216, 16, v204
	v_and_b32_e32 v217, 0xffff0000, v204
	v_lshlrev_b32_e32 v220, 16, v205
	v_and_b32_e32 v221, 0xffff0000, v205
	v_pk_add_f32 v[246:247], v[246:247], v[216:217]
	v_pk_add_f32 v[248:249], v[248:249], v[220:221]
	v_cvt_pk_bf16_f32 v172, v246, v247
	v_cvt_pk_bf16_f32 v173, v248, v249
	s_nop 1
	v_permlane16_swap_b32_e32 v170, v172
	v_permlane16_swap_b32_e32 v171, v173
	global_store_dwordx4 v[152:153], v[170:173], off offset:0
	s_waitcnt vmcnt(17)
	v_permlane16_swap_b32_e32 v174, v176
	v_permlane16_swap_b32_e32 v175, v177
	v_permlane16_swap_b32_e32 v206, v208
	v_permlane16_swap_b32_e32 v207, v209
	v_lshlrev_b32_e32 v246, 16, v174
	v_and_b32_e32 v247, 0xffff0000, v174
	v_lshlrev_b32_e32 v248, 16, v175
	v_and_b32_e32 v249, 0xffff0000, v175
	v_pk_mul_f32 v[246:247], v[46:47], v[246:247]
	v_pk_mul_f32 v[248:249], v[48:49], v[248:249]
	v_lshlrev_b32_e32 v216, 16, v206
	v_and_b32_e32 v217, 0xffff0000, v206
	v_lshlrev_b32_e32 v220, 16, v207
	v_and_b32_e32 v221, 0xffff0000, v207
	v_pk_add_f32 v[246:247], v[246:247], v[216:217]
	v_pk_add_f32 v[248:249], v[248:249], v[220:221]
	v_cvt_pk_bf16_f32 v174, v246, v247
	v_cvt_pk_bf16_f32 v175, v248, v249
	v_lshlrev_b32_e32 v246, 16, v176
	v_and_b32_e32 v247, 0xffff0000, v176
	v_lshlrev_b32_e32 v248, 16, v177
	v_and_b32_e32 v249, 0xffff0000, v177
	v_pk_mul_f32 v[246:247], v[42:43], v[246:247]
	v_pk_mul_f32 v[248:249], v[44:45], v[248:249]
	v_lshlrev_b32_e32 v216, 16, v208
	v_and_b32_e32 v217, 0xffff0000, v208
	v_lshlrev_b32_e32 v220, 16, v209
	v_and_b32_e32 v221, 0xffff0000, v209
	v_pk_add_f32 v[246:247], v[246:247], v[216:217]
	v_pk_add_f32 v[248:249], v[248:249], v[220:221]
	v_cvt_pk_bf16_f32 v176, v246, v247
	v_cvt_pk_bf16_f32 v177, v248, v249
	s_nop 1
	v_permlane16_swap_b32_e32 v174, v176
	v_permlane16_swap_b32_e32 v175, v177
	global_store_dwordx4 v[154:155], v[174:177], off offset:0
	s_waitcnt vmcnt(15)
	v_permlane16_swap_b32_e32 v178, v180
	v_permlane16_swap_b32_e32 v179, v181
	v_permlane16_swap_b32_e32 v226, v228
	v_permlane16_swap_b32_e32 v227, v229
	v_lshlrev_b32_e32 v246, 16, v178
	v_and_b32_e32 v247, 0xffff0000, v178
	v_lshlrev_b32_e32 v248, 16, v179
	v_and_b32_e32 v249, 0xffff0000, v179
	v_pk_mul_f32 v[246:247], v[38:39], v[246:247]
	v_pk_mul_f32 v[248:249], v[40:41], v[248:249]
	v_lshlrev_b32_e32 v216, 16, v226
	v_and_b32_e32 v217, 0xffff0000, v226
	v_lshlrev_b32_e32 v220, 16, v227
	v_and_b32_e32 v221, 0xffff0000, v227
	v_pk_add_f32 v[246:247], v[246:247], v[216:217]
	v_pk_add_f32 v[248:249], v[248:249], v[220:221]
	v_cvt_pk_bf16_f32 v178, v246, v247
	v_cvt_pk_bf16_f32 v179, v248, v249
	v_lshlrev_b32_e32 v246, 16, v180
	v_and_b32_e32 v247, 0xffff0000, v180
	v_lshlrev_b32_e32 v248, 16, v181
	v_and_b32_e32 v249, 0xffff0000, v181
	v_pk_mul_f32 v[246:247], v[34:35], v[246:247]
	v_pk_mul_f32 v[248:249], v[36:37], v[248:249]
	v_lshlrev_b32_e32 v216, 16, v228
	v_and_b32_e32 v217, 0xffff0000, v228
	v_lshlrev_b32_e32 v220, 16, v229
	v_and_b32_e32 v221, 0xffff0000, v229
	v_pk_add_f32 v[246:247], v[246:247], v[216:217]
	v_pk_add_f32 v[248:249], v[248:249], v[220:221]
	v_cvt_pk_bf16_f32 v180, v246, v247
	v_cvt_pk_bf16_f32 v181, v248, v249
	s_nop 1
	v_permlane16_swap_b32_e32 v178, v180
	v_permlane16_swap_b32_e32 v179, v181
	global_store_dwordx4 v[156:157], v[178:181], off offset:0
	s_waitcnt vmcnt(13)
	v_permlane16_swap_b32_e32 v182, v184
	v_permlane16_swap_b32_e32 v183, v185
	v_permlane16_swap_b32_e32 v230, v232
	v_permlane16_swap_b32_e32 v231, v233
	v_lshlrev_b32_e32 v246, 16, v182
	v_and_b32_e32 v247, 0xffff0000, v182
	v_lshlrev_b32_e32 v248, 16, v183
	v_and_b32_e32 v249, 0xffff0000, v183
	v_pk_mul_f32 v[246:247], v[30:31], v[246:247]
	v_pk_mul_f32 v[248:249], v[32:33], v[248:249]
	v_lshlrev_b32_e32 v216, 16, v230
	v_and_b32_e32 v217, 0xffff0000, v230
	v_lshlrev_b32_e32 v220, 16, v231
	v_and_b32_e32 v221, 0xffff0000, v231
	v_pk_add_f32 v[246:247], v[246:247], v[216:217]
	v_pk_add_f32 v[248:249], v[248:249], v[220:221]
	v_cvt_pk_bf16_f32 v182, v246, v247
	v_cvt_pk_bf16_f32 v183, v248, v249
	v_lshlrev_b32_e32 v246, 16, v184
	v_and_b32_e32 v247, 0xffff0000, v184
	v_lshlrev_b32_e32 v248, 16, v185
	v_and_b32_e32 v249, 0xffff0000, v185
	v_pk_mul_f32 v[246:247], v[26:27], v[246:247]
	v_pk_mul_f32 v[248:249], v[28:29], v[248:249]
	v_lshlrev_b32_e32 v216, 16, v232
	v_and_b32_e32 v217, 0xffff0000, v232
	v_lshlrev_b32_e32 v220, 16, v233
	v_and_b32_e32 v221, 0xffff0000, v233
	v_pk_add_f32 v[246:247], v[246:247], v[216:217]
	v_pk_add_f32 v[248:249], v[248:249], v[220:221]
	v_cvt_pk_bf16_f32 v184, v246, v247
	v_cvt_pk_bf16_f32 v185, v248, v249
	s_nop 1
	v_permlane16_swap_b32_e32 v182, v184
	v_permlane16_swap_b32_e32 v183, v185
	global_store_dwordx4 v[158:159], v[182:185], off offset:256
	s_waitcnt vmcnt(11)
	v_permlane16_swap_b32_e32 v186, v188
	v_permlane16_swap_b32_e32 v187, v189
	v_permlane16_swap_b32_e32 v234, v236
	v_permlane16_swap_b32_e32 v235, v237
	v_lshlrev_b32_e32 v246, 16, v186
	v_and_b32_e32 v247, 0xffff0000, v186
	v_lshlrev_b32_e32 v248, 16, v187
	v_and_b32_e32 v249, 0xffff0000, v187
	v_pk_mul_f32 v[246:247], v[22:23], v[246:247]
	v_pk_mul_f32 v[248:249], v[24:25], v[248:249]
	v_lshlrev_b32_e32 v216, 16, v234
	v_and_b32_e32 v217, 0xffff0000, v234
	v_lshlrev_b32_e32 v220, 16, v235
	v_and_b32_e32 v221, 0xffff0000, v235
	v_pk_add_f32 v[246:247], v[246:247], v[216:217]
	v_pk_add_f32 v[248:249], v[248:249], v[220:221]
	v_cvt_pk_bf16_f32 v186, v246, v247
	v_cvt_pk_bf16_f32 v187, v248, v249
	v_lshlrev_b32_e32 v246, 16, v188
	v_and_b32_e32 v247, 0xffff0000, v188
	v_lshlrev_b32_e32 v248, 16, v189
	v_and_b32_e32 v249, 0xffff0000, v189
	v_pk_mul_f32 v[246:247], v[18:19], v[246:247]
	v_pk_mul_f32 v[248:249], v[20:21], v[248:249]
	v_lshlrev_b32_e32 v216, 16, v236
	v_and_b32_e32 v217, 0xffff0000, v236
	v_lshlrev_b32_e32 v220, 16, v237
	v_and_b32_e32 v221, 0xffff0000, v237
	v_pk_add_f32 v[246:247], v[246:247], v[216:217]
	v_pk_add_f32 v[248:249], v[248:249], v[220:221]
	v_cvt_pk_bf16_f32 v188, v246, v247
	v_cvt_pk_bf16_f32 v189, v248, v249
	s_nop 1
	v_permlane16_swap_b32_e32 v186, v188
	v_permlane16_swap_b32_e32 v187, v189
	global_store_dwordx4 v[160:161], v[186:189], off offset:256
	s_waitcnt vmcnt(9)
	v_permlane16_swap_b32_e32 v190, v192
	v_permlane16_swap_b32_e32 v191, v193
	v_permlane16_swap_b32_e32 v238, v240
	v_permlane16_swap_b32_e32 v239, v241
	v_lshlrev_b32_e32 v246, 16, v190
	v_and_b32_e32 v247, 0xffff0000, v190
	v_lshlrev_b32_e32 v248, 16, v191
	v_and_b32_e32 v249, 0xffff0000, v191
	v_pk_mul_f32 v[246:247], v[14:15], v[246:247]
	v_pk_mul_f32 v[248:249], v[16:17], v[248:249]
	v_lshlrev_b32_e32 v216, 16, v238
	v_and_b32_e32 v217, 0xffff0000, v238
	v_lshlrev_b32_e32 v220, 16, v239
	v_and_b32_e32 v221, 0xffff0000, v239
	v_pk_add_f32 v[246:247], v[246:247], v[216:217]
	v_pk_add_f32 v[248:249], v[248:249], v[220:221]
	v_cvt_pk_bf16_f32 v190, v246, v247
	v_cvt_pk_bf16_f32 v191, v248, v249
	v_lshlrev_b32_e32 v246, 16, v192
	v_and_b32_e32 v247, 0xffff0000, v192
	v_lshlrev_b32_e32 v248, 16, v193
	v_and_b32_e32 v249, 0xffff0000, v193
	v_pk_mul_f32 v[246:247], v[10:11], v[246:247]
	v_pk_mul_f32 v[248:249], v[12:13], v[248:249]
	v_lshlrev_b32_e32 v216, 16, v240
	v_and_b32_e32 v217, 0xffff0000, v240
	v_lshlrev_b32_e32 v220, 16, v241
	v_and_b32_e32 v221, 0xffff0000, v241
	v_pk_add_f32 v[246:247], v[246:247], v[216:217]
	v_pk_add_f32 v[248:249], v[248:249], v[220:221]
	v_cvt_pk_bf16_f32 v192, v246, v247
	v_cvt_pk_bf16_f32 v193, v248, v249
	s_nop 1
	v_permlane16_swap_b32_e32 v190, v192
	v_permlane16_swap_b32_e32 v191, v193
	global_store_dwordx4 v[162:163], v[190:193], off offset:256
	s_waitcnt vmcnt(7)
	v_permlane16_swap_b32_e32 v194, v196
	v_permlane16_swap_b32_e32 v195, v197
	v_permlane16_swap_b32_e32 v242, v244
	v_permlane16_swap_b32_e32 v243, v245
	v_lshlrev_b32_e32 v246, 16, v194
	v_and_b32_e32 v247, 0xffff0000, v194
	v_lshlrev_b32_e32 v248, 16, v195
	v_and_b32_e32 v249, 0xffff0000, v195
	v_pk_mul_f32 v[246:247], v[6:7], v[246:247]
	v_pk_mul_f32 v[248:249], v[8:9], v[248:249]
	v_lshlrev_b32_e32 v216, 16, v242
	v_and_b32_e32 v217, 0xffff0000, v242
	v_lshlrev_b32_e32 v220, 16, v243
	v_and_b32_e32 v221, 0xffff0000, v243
	v_pk_add_f32 v[246:247], v[246:247], v[216:217]
	v_pk_add_f32 v[248:249], v[248:249], v[220:221]
	v_cvt_pk_bf16_f32 v194, v246, v247
	v_cvt_pk_bf16_f32 v195, v248, v249
	v_lshlrev_b32_e32 v246, 16, v196
	v_and_b32_e32 v247, 0xffff0000, v196
	v_lshlrev_b32_e32 v248, 16, v197
	v_and_b32_e32 v249, 0xffff0000, v197
	v_pk_mul_f32 v[246:247], v[2:3], v[246:247]
	v_pk_mul_f32 v[248:249], v[4:5], v[248:249]
	v_lshlrev_b32_e32 v216, 16, v244
	v_and_b32_e32 v217, 0xffff0000, v244
	v_lshlrev_b32_e32 v220, 16, v245
	v_and_b32_e32 v221, 0xffff0000, v245
	v_pk_add_f32 v[246:247], v[246:247], v[216:217]
	v_pk_add_f32 v[248:249], v[248:249], v[220:221]
	v_cvt_pk_bf16_f32 v196, v246, v247
	v_cvt_pk_bf16_f32 v197, v248, v249
	s_nop 1
	v_permlane16_swap_b32_e32 v194, v196
	v_permlane16_swap_b32_e32 v195, v197
	global_store_dwordx4 v[164:165], v[194:197], off offset:256
.Lmix_done:
	s_add_i32 s27, s27, 1
	s_mov_b64 s[0:1], 0
	s_branch .LBB0_73

.LBB0_315:
	s_andn2_b64 vcc, exec, s[0:1]
	s_cbranch_vccnz .LBB0_981
	v_readlane_b32 s0, v252, 61
	v_readlane_b32 s1, v252, 62
	s_lshl_b64 s[0:1], s[0:1], 24
	v_writelane_b32 v253, s0, 12
	v_readlane_b32 s2, v251, 23
	v_readlane_b32 s16, v251, 1
	v_writelane_b32 v253, s1, 13
	v_readlane_b32 s30, v251, 15
	v_readlane_b32 s0, v253, 8
	v_readlane_b32 s1, v253, 9
	s_lshl_b64 s[0:1], s[0:1], 2
	s_add_u32 s8, s2, s0
	v_readlane_b32 s2, v251, 24
	s_addc_u32 s9, s2, s1
	v_readlane_b32 s2, v251, 25
	v_writelane_b32 v253, s8, 14
	s_add_u32 s2, s2, s0
	v_readlane_b32 s0, v251, 26
	v_writelane_b32 v253, s9, 15
	s_addc_u32 s3, s0, s1
	v_readlane_b32 s31, v251, 16
	v_writelane_b32 v253, s2, 16
	s_mov_b64 s[0:1], s[30:31]
	s_waitcnt vmcnt(0)
	v_mov_b32_e32 v6, v211
	v_writelane_b32 v253, s3, 17
	s_add_u32 s2, s0, 0x23e96200
	s_addc_u32 s3, s1, 0
	v_writelane_b32 v253, s2, 18
	v_readlane_b32 s17, v251, 2
	v_bfe_u32 v8, v6, 5, 1
	v_writelane_b32 v253, s3, 19
	s_add_u32 s2, s0, 0x22982200
	s_addc_u32 s3, s1, 0
	v_writelane_b32 v253, s2, 20
	v_lshlrev_b32_e32 v0, 4, v8
	v_ashrrev_i32_e32 v237, 6, v6
	v_writelane_b32 v253, s3, 21
	s_add_u32 s2, s0, 0x22d82200
	s_addc_u32 s3, s1, 0
	v_writelane_b32 v253, s2, 22
	v_lshl_add_u64 v[2:3], s[0:1], 0, v[0:1]
	v_and_b32_e32 v148, 63, v6
	v_writelane_b32 v253, s3, 23
	s_add_u32 s2, s0, 0x23d82200
	s_addc_u32 s3, s1, 0
	v_writelane_b32 v253, s2, 24
	v_and_b32_e32 v7, 31, v6
	v_lshlrev_b32_e32 v0, 5, v237
	v_writelane_b32 v253, s3, 25
	v_readlane_b32 s2, v252, 56
	v_readlane_b32 s3, v252, 57
	s_lshl_b64 s[8:9], s[2:3], 2
	s_add_u32 s2, s0, s8
	v_writelane_b32 v253, s8, 26
	s_addc_u32 s3, s1, s9
	s_add_u32 s2, s2, 0x23f9a200
	s_movk_i32 s0, 0x4050
	v_writelane_b32 v253, s9, 27
	s_addc_u32 s3, s3, 0
	v_mul_lo_u32 v9, v237, s0
	s_movk_i32 s0, 0x500
	v_writelane_b32 v253, s2, 28
	v_mul_lo_u32 v10, v237, s0
	v_readlane_b32 s0, v252, 25
	v_writelane_b32 v253, s3, 29
	v_or_b32_e32 v240, v0, v7
	v_add_u32_e32 v242, s0, v10
	v_cmp_eq_u32_e64 s[0:1], 0, v148
	v_bfe_u32 v12, v6, 2, 2
	v_add_u32_e32 v241, 0, v9
	v_writelane_b32 v253, s0, 30
	v_lshlrev_b64 v[4:5], v6, -1
	v_not_b32_e32 v209, v5
	v_writelane_b32 v253, s1, 31
	v_cmp_gt_u32_e64 s[0:1], 2, v148
	v_lshlrev_b32_e32 v5, 3, v6
	v_and_b32_e32 v188, 24, v5
	v_writelane_b32 v253, s0, 32
	v_lshlrev_b32_e32 v11, 2, v148
	v_and_b32_e32 v238, 7, v6
	v_writelane_b32 v253, s1, 33
	v_cmp_gt_u32_e64 s[0:1], 4, v148
	v_not_b32_e32 v212, v4
	v_and_b32_e32 v4, 15, v6
	v_writelane_b32 v253, s0, 34
	v_mul_u32_u24_e32 v190, 0x108, v4
	v_lshlrev_b32_e32 v150, 3, v8
	v_writelane_b32 v253, s1, 35
	v_cmp_gt_u32_e64 s[0:1], 8, v148
	v_lshlrev_b32_e32 v239, 2, v8
	v_add_u32_e32 v243, v241, v11
	v_writelane_b32 v253, s0, 36
	v_cmp_gt_u32_e64 s[16:17], 4, v4
	v_lshlrev_b32_e32 v214, 6, v4
	v_writelane_b32 v253, s1, 37
	v_cmp_gt_u32_e64 s[0:1], 32, v148
	v_lshlrev_b32_e32 v218, 3, v4
	v_lshlrev_b32_e32 v177, 4, v4
	v_writelane_b32 v253, s0, 38
	v_add_u32_e32 v189, v242, v11
	v_lshl_or_b32 v197, v4, 2, v10
	v_writelane_b32 v253, s1, 39
	v_readlane_b32 s0, v252, 26
	v_mov_b32_e32 v4, v1
	v_mov_b32_e32 v15, v1
	v_add_u32_e32 v248, s0, v0
	v_bfe_u32 v0, v6, 4, 2
	v_lshlrev_b32_e32 v216, 3, v0
	s_movk_i32 s0, 0x120
	v_or_b32_e32 v12, v216, v12
	v_mad_u32_u24 v217, v0, s0, v241
	v_mad_u32_u24 v185, v12, s0, v241
	s_movk_i32 s0, 0xfef0
	v_lshlrev_b32_e32 v13, 2, v0
	v_mul_u32_u24_e32 v14, 0x120, v0
	v_mul_i32_i24_e32 v5, 0xfffffef0, v0
	v_mad_i32_i24 v187, v0, s0, v217
	v_lshlrev_b32_e32 v0, 4, v6
	v_and_b32_e32 v0, 0x180, v0
	v_lshl_add_u64 v[2:3], v[2:3], 0, v[0:1]
	s_mov_b64 s[0:1], 0x8100000
	v_lshl_add_u64 v[220:221], v[2:3], 0, s[0:1]
	v_lshlrev_b32_e32 v0, 7, v237
	s_mov_b32 s0, 0x10140
	v_mad_u32_u24 v0, v8, s0, v0
	v_lshlrev_b32_e32 v2, 2, v7
	v_add3_u32 v192, v0, v2, 0
	v_add_u32_e32 v0, v9, v11
	s_movk_i32 s0, 0x210
	v_mad_u32_u24 v200, v148, 28, v0
	v_add_u32_e32 v193, 0, v0
	v_mad_u32_u24 v0, v238, s0, v9
	v_lshrrev_b32_e32 v2, 2, v6
	v_and_or_b32 v0, v2, 14, v0
	s_add_i32 s0, 0, 0x2400
	v_add_u32_e32 v196, s0, v0
	v_add3_u32 v0, v14, v5, v9
	v_lshlrev_b32_e32 v2, 1, v190
	s_movk_i32 s0, 0x2400
	v_add_u32_e32 v249, v248, v11
	v_add_u32_e32 v250, v242, v13
	v_add3_u32 v195, v0, v2, s0
	v_or_b32_e32 v198, v10, v13
	v_mov_b32_e32 v2, v1
	v_mov_b32_e32 v3, v1
	v_mov_b32_e32 v5, v1
	v_mov_b32_e32 v6, v1
	v_mov_b32_e32 v7, v1
	v_mov_b32_e32 v8, v1
	v_mov_b32_e32 v9, v1
	v_mov_b32_e32 v10, v1
	v_mov_b32_e32 v11, v1
	v_mov_b32_e32 v12, v1
	v_mov_b32_e32 v13, v1
	v_mov_b32_e32 v14, v1
	v_mov_b32_e32 v0, v1
	v_mov_b64_e32 v[16:17], v[14:15]
	s_movk_i32 s4, 0x610
	v_or_b32_e32 v244, 64, v148
	v_or_b32_e32 v245, 0x80, v148
	v_or_b32_e32 v246, 0xc0, v148
	v_or_b32_e32 v149, 0x100, v148
	v_or_b32_e32 v152, 0x140, v148
	v_or_b32_e32 v151, 0x180, v148
	v_or_b32_e32 v154, 0x1c0, v148
	v_or_b32_e32 v153, 0x200, v148
	v_or_b32_e32 v156, 0x240, v148
	v_or_b32_e32 v155, 0x280, v148
	v_or_b32_e32 v158, 0x2c0, v148
	v_or_b32_e32 v157, 0x300, v148
	v_or_b32_e32 v160, 0x340, v148
	v_or_b32_e32 v159, 0x380, v148
	v_or_b32_e32 v162, 0x3c0, v148
	v_or_b32_e32 v161, 0x400, v148
	v_or_b32_e32 v164, 0x440, v148
	v_or_b32_e32 v163, 0x480, v148
	v_or_b32_e32 v166, 0x4c0, v148
	v_or_b32_e32 v165, 0x500, v148
	v_or_b32_e32 v168, 0x540, v148
	v_or_b32_e32 v167, 0x580, v148
	v_or_b32_e32 v170, 0x5c0, v148
	v_or_b32_e32 v169, 0x600, v148
	v_or_b32_e32 v172, 0x640, v148
	v_or_b32_e32 v171, 0x680, v148
	v_or_b32_e32 v174, 0x6c0, v148
	v_or_b32_e32 v173, 0x700, v148
	v_or_b32_e32 v176, 0x740, v148
	v_or_b32_e32 v175, 0x780, v148
	v_or_b32_e32 v178, 0x7c0, v148
	v_or_b32_e32 v247, 0x800, v148
	v_or_b32_e32 v147, 0x840, v148
	v_or_b32_e32 v146, 0x880, v148
	v_or_b32_e32 v235, 0x8c0, v148
	v_or_b32_e32 v234, 0x900, v148
	v_or_b32_e32 v236, 0x980, v148
	v_or_b32_e32 v201, 0xe40, v148
	v_or_b32_e32 v204, 0xe80, v148
	v_or_b32_e32 v203, 0xec0, v148
	v_or_b32_e32 v206, 0xf00, v148
	v_or_b32_e32 v205, 0xf40, v148
	v_or_b32_e32 v208, 0xf80, v148
	v_or_b32_e32 v207, 0xfc0, v148
	v_or_b32_e32 v210, 0x1000, v148
	v_cmp_gt_u32_e64 s[12:13], 16, v148
	v_add_u32_e32 v180, 0x480, v217
	v_add_u32_e32 v179, 0x900, v217
	v_add_u32_e32 v182, 0xd80, v217
	v_add_u32_e32 v181, 0x1200, v217
	v_add_u32_e32 v184, 0x1680, v217
	v_add_u32_e32 v183, 0x1b00, v217
	v_add_u32_e32 v186, 0x1f80, v217
	s_mov_b64 s[8:9], 0
	v_lshlrev_b32_e32 v222, 1, v148
	v_mov_b64_e32 v[14:15], v[12:13]
	v_mov_b64_e32 v[12:13], v[10:11]
	v_mov_b64_e32 v[10:11], v[8:9]
	v_mov_b64_e32 v[8:9], v[6:7]
	v_mov_b64_e32 v[6:7], v[4:5]
	v_mov_b64_e32 v[4:5], v[2:3]
	v_mov_b64_e32 v[2:3], v[0:1]
	v_readlane_b32 s18, v251, 3
	v_readlane_b32 s19, v251, 4
	v_readlane_b32 s20, v251, 5
	v_readlane_b32 s21, v251, 6
	v_readlane_b32 s22, v251, 7
	v_readlane_b32 s23, v251, 8
	v_readlane_b32 s24, v251, 9
	v_readlane_b32 s25, v251, 10
	v_readlane_b32 s26, v251, 11
	v_readlane_b32 s27, v251, 12
	v_readlane_b32 s28, v251, 13
	v_readlane_b32 s29, v251, 14
	s_mov_b32 s101, 0
	s_branch .LBB0_319

.LBB0_319:
	s_waitcnt lgkmcnt(0)
	s_barrier
	s_mov_b64 s[0:1], exec
	v_readlane_b32 s2, v251, 19
	v_readlane_b32 s3, v251, 20
	s_and_b64 s[2:3], s[0:1], s[2:3]
	s_mov_b64 exec, s[2:3]
	s_cbranch_execz .LBB0_321
	v_readlane_b32 s10, v253, 28
	v_readlane_b32 s11, v253, 29
	s_mov_b64 s[2:3], src_shared_base
	s_add_i32 s2, 0, 0x22ff0
	v_mov_b64_e32 v[18:19], s[10:11]
	s_cmp_eq_u32 s101, 0
	s_cbranch_scc1 .Ldq_atomic
	s_waitcnt vmcnt(0)
	v_mov_b32_e32 v0, v215
	s_branch .Ldq_have
.Ldq_atomic:
	flat_atomic_add v0, v[18:19], v213 sc0
.Ldq_have:
	s_cmp_lg_u32 s2, -1
	s_cselect_b32 s2, s2, 0
	s_cselect_b32 s3, s3, 0
	v_mov_b32_e32 v18, s2
	v_mov_b32_e32 v19, s3
	s_waitcnt vmcnt(0) lgkmcnt(0)
	flat_store_dword v[18:19], v0 sc0 sc1
	s_waitcnt vmcnt(0)

.LBB0_354:
	s_or_b64 exec, exec, s[2:3]
	v_readlane_b32 s42, v253, 28
	v_readlane_b32 s43, v253, 29
	v_readlane_b32 s46, v251, 19
	v_readlane_b32 s47, v251, 20
	s_mov_b64 s[44:45], exec
	s_nop 3
	s_and_b64 exec, exec, s[46:47]
	global_atomic_add v215, v1, v213, s[42:43] sc0
	s_mov_b64 exec, s[44:45]
	s_mov_b32 s101, 1
	s_movk_i32 s0, 0x100
	v_cmp_lt_i32_e32 vcc, s0, v139
	s_waitcnt lgkmcnt(0)
	s_barrier
	s_and_saveexec_b64 s[0:1], vcc
	s_xor_b64 s[0:1], exec, s[0:1]
	v_writelane_b32 v253, s0, 42
	s_nop 1
	v_writelane_b32 v253, s1, 43
	s_cbranch_execz .LBB0_681
	v_cmp_lt_u32_e64 s[0:1], v149, v139
	ds_read2st64_b32 v[20:21], v243 offset1:1
	ds_read_b32 v19, v243 offset:512
	v_writelane_b32 v253, s0, 44
	v_add_u32_e32 v0, -1, v139
	v_min_u32_e32 v18, v149, v0
	v_writelane_b32 v253, s1, 45
	v_cmp_lt_u32_e64 s[0:1], v152, v139
	v_lshl_add_u32 v25, v18, 2, v241
	v_min_u32_e32 v18, v152, v0
	v_writelane_b32 v253, s0, 46
	s_waitcnt lgkmcnt(0)
	v_mov_b32_e32 v28, v21
	v_mov_b32_e32 v29, v20
	v_writelane_b32 v253, s1, 47
	v_cmp_lt_u32_e64 s[0:1], v151, v139
	v_lshl_add_u32 v26, v18, 2, v241
	v_min_u32_e32 v18, v151, v0
	v_writelane_b32 v253, s0, 48
	v_pk_add_f32 v[20:21], v[28:29], 0 op_sel_hi:[1,0]
	v_lshl_add_u32 v22, v18, 2, v241
	v_writelane_b32 v253, s1, 49
	v_cmp_lt_u32_e64 s[0:1], v154, v139
	v_min_u32_e32 v18, v154, v0
	v_and_b32_e32 v29, 0x7fffffff, v21
	v_writelane_b32 v253, s0, 50
	v_and_b32_e32 v28, 0x7fffffff, v20
	v_lshl_add_u32 v24, v18, 2, v241
	v_writelane_b32 v253, s1, 51
	s_movk_i32 s0, 0x200
	v_cmp_lt_u32_e32 vcc, s0, v139
	v_xor_b32_e32 v18, -1, v21
	v_pk_add_f32 v[28:29], v[28:29], 0 neg_lo:[1,1] neg_hi:[1,1]
	v_cmp_gt_i32_e64 s[0:1], 0, v21
	v_xor_b32_e32 v23, -1, v20
	s_waitcnt vmcnt(0)
	v_cndmask_b32_e64 v67, v29, v18, s[0:1]
	v_cmp_gt_i32_e64 s[0:1], 0, v20
	s_nop 1
	v_cndmask_b32_e64 v62, v28, v23, s[0:1]
	s_and_saveexec_b64 s[0:1], vcc
	s_xor_b64 s[0:1], exec, s[0:1]
	v_writelane_b32 v253, s0, 52
	s_nop 1
	v_writelane_b32 v253, s1, 53
	s_cbranch_execz .LBB0_660
	s_movk_i32 s0, 0x400
	v_cmp_lt_u32_e32 vcc, s0, v139
	v_cmp_lt_u32_e64 s[0:1], v153, v139
	v_min_u32_e32 v18, v153, v0
	v_lshl_add_u32 v28, v18, 2, v241
	v_writelane_b32 v253, s0, 54
	v_min_u32_e32 v18, v156, v0
	v_lshl_add_u32 v29, v18, 2, v241
	v_writelane_b32 v253, s1, 55
	v_cmp_lt_u32_e64 s[0:1], v156, v139
	v_min_u32_e32 v18, v155, v0
	v_lshl_add_u32 v27, v18, 2, v241
	v_writelane_b32 v253, s0, 56
	v_min_u32_e32 v18, v158, v0
	v_lshl_add_u32 v32, v18, 2, v241
	v_writelane_b32 v253, s1, 57
	v_cmp_lt_u32_e64 s[0:1], v155, v139
	v_min_u32_e32 v18, v157, v0
	v_lshl_add_u32 v23, v18, 2, v241
	v_writelane_b32 v253, s0, 58
	v_min_u32_e32 v18, v160, v0
	v_lshl_add_u32 v30, v18, 2, v241
	v_writelane_b32 v253, s1, 59
	v_cmp_lt_u32_e64 s[0:1], v158, v139
	v_min_u32_e32 v18, v159, v0
	v_lshl_add_u32 v20, v18, 2, v241
	v_writelane_b32 v253, s0, 60
	v_min_u32_e32 v18, v162, v0
	v_cmp_lt_u32_e64 s[58:59], v159, v139
	v_writelane_b32 v253, s1, 61
	v_cmp_lt_u32_e64 s[0:1], v157, v139
	v_lshl_add_u32 v21, v18, 2, v241
	s_nop 0
	v_writelane_b32 v253, s0, 62
	s_nop 1
	v_writelane_b32 v253, s1, 63
	v_cmp_lt_u32_e64 s[0:1], v160, v139
	s_nop 1
	v_writelane_b32 v254, s0, 0
	s_nop 1
	v_writelane_b32 v254, s1, 1
	v_cmp_lt_u32_e64 s[0:1], v162, v139
	s_nop 1
	v_writelane_b32 v254, s0, 2
	s_nop 1
	v_writelane_b32 v254, s1, 3
	s_and_saveexec_b64 s[0:1], vcc
	s_xor_b64 s[0:1], exec, s[0:1]
	v_writelane_b32 v254, s0, 4
	s_nop 1
	v_writelane_b32 v254, s1, 5
	s_cbranch_execz .LBB0_623
	v_min_u32_e32 v18, v161, v0
	v_lshl_add_u32 v31, v18, 2, v241
	v_min_u32_e32 v18, v164, v0
	v_lshl_add_u32 v33, v18, 2, v241
	v_min_u32_e32 v18, v163, v0
	v_lshl_add_u32 v36, v18, 2, v241
	v_min_u32_e32 v18, v166, v0
	v_lshl_add_u32 v38, v18, 2, v241
	v_min_u32_e32 v18, v165, v0
	v_lshl_add_u32 v39, v18, 2, v241
	v_min_u32_e32 v18, v168, v0
	v_lshl_add_u32 v40, v18, 2, v241
	v_min_u32_e32 v18, v167, v0
	v_lshl_add_u32 v41, v18, 2, v241
	v_min_u32_e32 v18, v170, v0
	v_lshl_add_u32 v42, v18, 2, v241
	v_min_u32_e32 v18, v169, v0
	v_lshl_add_u32 v43, v18, 2, v241
	v_min_u32_e32 v18, v172, v0
	v_lshl_add_u32 v44, v18, 2, v241
	v_min_u32_e32 v18, v171, v0
	v_lshl_add_u32 v45, v18, 2, v241
	v_min_u32_e32 v18, v174, v0
	v_lshl_add_u32 v46, v18, 2, v241
	v_min_u32_e32 v18, v173, v0
	v_lshl_add_u32 v47, v18, 2, v241
	v_min_u32_e32 v18, v176, v0
	v_lshl_add_u32 v48, v18, 2, v241
	v_min_u32_e32 v18, v175, v0
	v_lshl_add_u32 v49, v18, 2, v241
	v_min_u32_e32 v18, v178, v0
	v_lshl_add_u32 v50, v18, 2, v241
	ds_read_b32 v18, v243 offset:768
	ds_read_b32 v35, v31
	ds_read_b32 v34, v33
	ds_read_b32 v37, v36
	ds_read_b32 v36, v38
	ds_read_b32 v39, v39
	ds_read_b32 v38, v40
	ds_read_b32 v31, v41
	s_waitcnt lgkmcnt(7)
	v_pk_add_f32 v[18:19], v[18:19], 0 op_sel_hi:[1,0]
	s_movk_i32 s0, 0x800
	v_and_b32_e32 v41, 0x7fffffff, v19
	v_and_b32_e32 v40, 0x7fffffff, v18
	v_cmp_lt_u32_e32 vcc, s0, v139
	v_xor_b32_e32 v33, -1, v19
	v_pk_add_f32 v[40:41], v[40:41], 0 neg_lo:[1,1] neg_hi:[1,1]
	v_cmp_gt_i32_e64 s[0:1], 0, v19
	v_xor_b32_e32 v51, -1, v18
	s_nop 0
	v_cndmask_b32_e64 v89, v41, v33, s[0:1]
	v_cmp_gt_i32_e64 s[0:1], 0, v18
	s_nop 1
	v_cndmask_b32_e64 v88, v40, v51, s[0:1]
	ds_read_b32 v19, v25
	ds_read_b32 v18, v26
	ds_read_b32 v25, v22
	ds_read_b32 v24, v24
	ds_read_b32 v41, v28
	ds_read_b32 v40, v29
	ds_read_b32 v27, v27
	ds_read_b32 v22, v50
	s_waitcnt lgkmcnt(6)
	v_pk_add_f32 v[18:19], v[18:19], 0 op_sel_hi:[1,0]
	s_nop 0
	v_and_b32_e32 v29, 0x7fffffff, v19
	v_and_b32_e32 v28, 0x7fffffff, v18
	v_xor_b32_e32 v33, -1, v18
	v_pk_add_f32 v[28:29], v[28:29], 0 neg_lo:[1,1] neg_hi:[1,1]
	v_cmp_gt_i32_e64 s[0:1], 0, v18
	v_xor_b32_e32 v26, -1, v19
	s_nop 0
	v_cndmask_b32_e64 v18, v28, v33, s[0:1]
	v_cmp_gt_i32_e64 s[0:1], 0, v19
	s_nop 1
	v_cndmask_b32_e64 v19, v29, v26, s[0:1]
	v_readlane_b32 s0, v253, 44
	v_readlane_b32 s1, v253, 45
	s_nop 1
	v_cndmask_b32_e64 v87, 0, v19, s[0:1]
	v_readlane_b32 s0, v253, 46
	v_readlane_b32 s1, v253, 47
	s_nop 1
	v_cndmask_b32_e64 v86, 0, v18, s[0:1]
	s_waitcnt lgkmcnt(4)
	v_pk_add_f32 v[18:19], v[24:25], 0 op_sel_hi:[1,0]
	s_nop 0
	v_and_b32_e32 v25, 0x7fffffff, v19
	v_and_b32_e32 v24, 0x7fffffff, v18
	v_xor_b32_e32 v28, -1, v18
	v_pk_add_f32 v[24:25], v[24:25], 0 neg_lo:[1,1] neg_hi:[1,1]
	v_cmp_gt_i32_e64 s[0:1], 0, v18
	v_xor_b32_e32 v26, -1, v19
	s_nop 0
	v_cndmask_b32_e64 v18, v24, v28, s[0:1]
	v_cmp_gt_i32_e64 s[0:1], 0, v19
	s_nop 1
	v_cndmask_b32_e64 v19, v25, v26, s[0:1]
	v_readlane_b32 s0, v253, 48
	v_readlane_b32 s1, v253, 49
	s_nop 1
	v_cndmask_b32_e64 v84, 0, v19, s[0:1]
	v_readlane_b32 s0, v253, 50
	v_readlane_b32 s1, v253, 51
	s_nop 1
	v_cndmask_b32_e64 v83, 0, v18, s[0:1]
	s_waitcnt lgkmcnt(2)
	v_pk_add_f32 v[18:19], v[40:41], 0 op_sel_hi:[1,0]
	s_nop 0
	v_and_b32_e32 v25, 0x7fffffff, v19
	v_and_b32_e32 v24, 0x7fffffff, v18
	v_xor_b32_e32 v28, -1, v18
	v_pk_add_f32 v[24:25], v[24:25], 0 neg_lo:[1,1] neg_hi:[1,1]
	v_cmp_gt_i32_e64 s[0:1], 0, v18
	v_xor_b32_e32 v26, -1, v19
	s_nop 0
	v_cndmask_b32_e64 v18, v24, v28, s[0:1]
	v_cmp_gt_i32_e64 s[0:1], 0, v19
	s_nop 1
	v_cndmask_b32_e64 v19, v25, v26, s[0:1]
	v_readlane_b32 s0, v253, 54
	v_readlane_b32 s1, v253, 55
	s_nop 1
	v_cndmask_b32_e64 v82, 0, v19, s[0:1]
	v_readlane_b32 s0, v253, 56
	v_readlane_b32 s1, v253, 57
	s_nop 1
	v_cndmask_b32_e64 v81, 0, v18, s[0:1]
	ds_read_b32 v26, v32
	ds_read_b32 v19, v23
	ds_read_b32 v18, v30
	ds_read_b32 v25, v20
	ds_read_b32 v24, v21
	s_waitcnt lgkmcnt(4)
	v_pk_add_f32 v[20:21], v[26:27], 0 op_sel_hi:[1,0]
	s_waitcnt lgkmcnt(2)
	v_pk_add_f32 v[18:19], v[18:19], 0 op_sel_hi:[1,0]
	v_and_b32_e32 v27, 0x7fffffff, v21
	v_and_b32_e32 v26, 0x7fffffff, v20
	v_xor_b32_e32 v28, -1, v20
	v_pk_add_f32 v[26:27], v[26:27], 0 neg_lo:[1,1] neg_hi:[1,1]
	v_cmp_gt_i32_e64 s[0:1], 0, v20
	v_xor_b32_e32 v23, -1, v21
	s_nop 0
	v_cndmask_b32_e64 v20, v26, v28, s[0:1]
	v_cmp_gt_i32_e64 s[0:1], 0, v21
	v_xor_b32_e32 v26, -1, v18
	s_nop 0
	v_cndmask_b32_e64 v21, v27, v23, s[0:1]
	v_readlane_b32 s0, v253, 58
	v_readlane_b32 s1, v253, 59
	v_xor_b32_e32 v23, -1, v19
	s_nop 0
	v_cndmask_b32_e64 v80, 0, v21, s[0:1]
	v_readlane_b32 s0, v253, 60
	v_readlane_b32 s1, v253, 61
	v_and_b32_e32 v21, 0x7fffffff, v19
	s_nop 0
	v_cndmask_b32_e64 v79, 0, v20, s[0:1]
	v_and_b32_e32 v20, 0x7fffffff, v18
	v_pk_add_f32 v[20:21], v[20:21], 0 neg_lo:[1,1] neg_hi:[1,1]
	v_cmp_gt_i32_e64 s[0:1], 0, v18
	s_nop 1
	v_cndmask_b32_e64 v18, v20, v26, s[0:1]
	v_cmp_gt_i32_e64 s[0:1], 0, v19
	s_nop 1
	v_cndmask_b32_e64 v19, v21, v23, s[0:1]
	v_readlane_b32 s0, v253, 62
	v_readlane_b32 s1, v253, 63
	s_nop 1
	v_cndmask_b32_e64 v78, 0, v19, s[0:1]
	v_readlane_b32 s0, v254, 0
	v_readlane_b32 s1, v254, 1
	s_nop 1
	v_cndmask_b32_e64 v77, 0, v18, s[0:1]
	s_waitcnt lgkmcnt(0)
	v_pk_add_f32 v[18:19], v[24:25], 0 op_sel_hi:[1,0]
	s_nop 0
	v_and_b32_e32 v21, 0x7fffffff, v19
	v_and_b32_e32 v20, 0x7fffffff, v18
	v_xor_b32_e32 v24, -1, v18
	v_pk_add_f32 v[20:21], v[20:21], 0 neg_lo:[1,1] neg_hi:[1,1]
	v_cmp_gt_i32_e64 s[0:1], 0, v18
	v_xor_b32_e32 v23, -1, v19
	s_nop 0
	v_cndmask_b32_e64 v18, v20, v24, s[0:1]
	v_cmp_gt_i32_e64 s[0:1], 0, v19
	s_nop 1
	v_cndmask_b32_e64 v19, v21, v23, s[0:1]
	v_readlane_b32 s0, v254, 2
	v_readlane_b32 s1, v254, 3
	v_cndmask_b32_e64 v75, 0, v19, s[58:59]
	s_nop 0
	v_cndmask_b32_e64 v73, 0, v18, s[0:1]
	v_pk_add_f32 v[18:19], v[34:35], 0 op_sel_hi:[1,0]
	s_nop 0
	v_and_b32_e32 v21, 0x7fffffff, v19
	v_and_b32_e32 v20, 0x7fffffff, v18
	v_xor_b32_e32 v24, -1, v18
	v_pk_add_f32 v[20:21], v[20:21], 0 neg_lo:[1,1] neg_hi:[1,1]
	v_cmp_gt_i32_e64 s[0:1], 0, v18
	v_xor_b32_e32 v23, -1, v19
	s_nop 0
	v_cndmask_b32_e64 v18, v20, v24, s[0:1]
	v_cmp_gt_i32_e64 s[0:1], 0, v19
	s_nop 1
	v_cndmask_b32_e64 v19, v21, v23, s[0:1]
	v_cmp_lt_u32_e64 s[0:1], v161, v139
	s_nop 1
	v_cndmask_b32_e64 v69, 0, v19, s[0:1]
	v_cmp_lt_u32_e64 s[0:1], v164, v139
	s_nop 1
	v_cndmask_b32_e64 v64, 0, v18, s[0:1]
	v_pk_add_f32 v[18:19], v[36:37], 0 op_sel_hi:[1,0]
	s_nop 0
	v_and_b32_e32 v21, 0x7fffffff, v19
	v_and_b32_e32 v20, 0x7fffffff, v18
	v_xor_b32_e32 v24, -1, v18
	v_pk_add_f32 v[20:21], v[20:21], 0 neg_lo:[1,1] neg_hi:[1,1]
	v_cmp_gt_i32_e64 s[0:1], 0, v18
	v_xor_b32_e32 v23, -1, v19
	s_nop 0
	v_cndmask_b32_e64 v18, v20, v24, s[0:1]
	v_cmp_gt_i32_e64 s[0:1], 0, v19
	s_nop 1
	v_cndmask_b32_e64 v19, v21, v23, s[0:1]
	v_cmp_lt_u32_e64 s[0:1], v163, v139
	s_nop 1
	v_cndmask_b32_e64 v63, 0, v19, s[0:1]
	v_cmp_lt_u32_e64 s[0:1], v166, v139
	s_nop 1
	v_cndmask_b32_e64 v61, 0, v18, s[0:1]
	v_pk_add_f32 v[18:19], v[38:39], 0 op_sel_hi:[1,0]
	s_nop 0
	v_and_b32_e32 v21, 0x7fffffff, v19
	v_and_b32_e32 v20, 0x7fffffff, v18
	v_xor_b32_e32 v24, -1, v18
	v_pk_add_f32 v[20:21], v[20:21], 0 neg_lo:[1,1] neg_hi:[1,1]
	v_cmp_gt_i32_e64 s[0:1], 0, v18
	v_xor_b32_e32 v23, -1, v19
	s_nop 0
	v_cndmask_b32_e64 v18, v20, v24, s[0:1]
	v_cmp_gt_i32_e64 s[0:1], 0, v19
	s_nop 1
	v_cndmask_b32_e64 v19, v21, v23, s[0:1]
	v_cmp_lt_u32_e64 s[0:1], v165, v139
	s_nop 1
	v_cndmask_b32_e64 v60, 0, v19, s[0:1]
	v_cmp_lt_u32_e64 s[0:1], v168, v139
	s_nop 1
	v_cndmask_b32_e64 v59, 0, v18, s[0:1]
	ds_read_b32 v30, v42
	ds_read_b32 v19, v43
	ds_read_b32 v18, v44
	ds_read_b32 v21, v45
	ds_read_b32 v20, v46
	ds_read_b32 v25, v47
	ds_read_b32 v24, v48
	ds_read_b32 v23, v49
	s_waitcnt lgkmcnt(7)
	v_pk_add_f32 v[26:27], v[30:31], 0 op_sel_hi:[1,0]
	s_waitcnt lgkmcnt(5)
	v_pk_add_f32 v[18:19], v[18:19], 0 op_sel_hi:[1,0]
	v_and_b32_e32 v29, 0x7fffffff, v27
	v_and_b32_e32 v28, 0x7fffffff, v26
	v_xor_b32_e32 v31, -1, v26
	v_pk_add_f32 v[28:29], v[28:29], 0 neg_lo:[1,1] neg_hi:[1,1]
	v_cmp_gt_i32_e64 s[0:1], 0, v26
	v_xor_b32_e32 v30, -1, v27
	s_nop 0
	v_cndmask_b32_e64 v26, v28, v31, s[0:1]
	v_cmp_gt_i32_e64 s[0:1], 0, v27
	v_xor_b32_e32 v28, -1, v19
	s_nop 0
	v_cndmask_b32_e64 v27, v29, v30, s[0:1]
	v_cmp_lt_u32_e64 s[0:1], v167, v139
	v_xor_b32_e32 v29, -1, v18
	s_nop 0
	v_cndmask_b32_e64 v58, 0, v27, s[0:1]
	v_cmp_lt_u32_e64 s[0:1], v170, v139
	v_and_b32_e32 v27, 0x7fffffff, v19
	s_nop 0
	v_cndmask_b32_e64 v57, 0, v26, s[0:1]
	v_and_b32_e32 v26, 0x7fffffff, v18
	v_pk_add_f32 v[26:27], v[26:27], 0 neg_lo:[1,1] neg_hi:[1,1]
	v_cmp_gt_i32_e64 s[0:1], 0, v18
	s_nop 1
	v_cndmask_b32_e64 v18, v26, v29, s[0:1]
	v_cmp_gt_i32_e64 s[0:1], 0, v19
	s_nop 1
	v_cndmask_b32_e64 v19, v27, v28, s[0:1]
	v_cmp_lt_u32_e64 s[0:1], v169, v139
	s_nop 1
	v_cndmask_b32_e64 v56, 0, v19, s[0:1]
	v_cmp_lt_u32_e64 s[0:1], v172, v139
	s_nop 1
	v_cndmask_b32_e64 v55, 0, v18, s[0:1]
	s_waitcnt lgkmcnt(3)
	v_pk_add_f32 v[18:19], v[20:21], 0 op_sel_hi:[1,0]
	s_nop 0
	v_and_b32_e32 v21, 0x7fffffff, v19
	v_and_b32_e32 v20, 0x7fffffff, v18
	v_xor_b32_e32 v27, -1, v18
	v_pk_add_f32 v[20:21], v[20:21], 0 neg_lo:[1,1] neg_hi:[1,1]
	v_cmp_gt_i32_e64 s[0:1], 0, v18
	v_xor_b32_e32 v26, -1, v19
	s_nop 0
	v_cndmask_b32_e64 v18, v20, v27, s[0:1]
	v_cmp_gt_i32_e64 s[0:1], 0, v19
	s_nop 1
	v_cndmask_b32_e64 v19, v21, v26, s[0:1]
	v_cmp_lt_u32_e64 s[0:1], v171, v139
	s_nop 1
	v_cndmask_b32_e64 v54, 0, v19, s[0:1]
	v_cmp_lt_u32_e64 s[0:1], v174, v139
	s_nop 1
	v_cndmask_b32_e64 v53, 0, v18, s[0:1]
	s_waitcnt lgkmcnt(1)
	v_pk_add_f32 v[18:19], v[24:25], 0 op_sel_hi:[1,0]
	s_nop 0
	v_and_b32_e32 v21, 0x7fffffff, v19
	v_and_b32_e32 v20, 0x7fffffff, v18
	v_xor_b32_e32 v25, -1, v18
	v_pk_add_f32 v[20:21], v[20:21], 0 neg_lo:[1,1] neg_hi:[1,1]
	v_cmp_gt_i32_e64 s[0:1], 0, v18
	v_xor_b32_e32 v24, -1, v19
	s_nop 0
	v_cndmask_b32_e64 v18, v20, v25, s[0:1]
	v_cmp_gt_i32_e64 s[0:1], 0, v19
	s_nop 1
	v_cndmask_b32_e64 v19, v21, v24, s[0:1]
	v_cmp_lt_u32_e64 s[0:1], v173, v139
	s_nop 1
	v_cndmask_b32_e64 v52, 0, v19, s[0:1]
	v_cmp_lt_u32_e64 s[0:1], v176, v139
	s_nop 1
	v_cndmask_b32_e64 v51, 0, v18, s[0:1]
	s_waitcnt lgkmcnt(0)
	v_pk_add_f32 v[18:19], v[22:23], 0 op_sel_hi:[1,0]
	s_nop 0
	v_and_b32_e32 v21, 0x7fffffff, v19
	v_and_b32_e32 v20, 0x7fffffff, v18
	v_xor_b32_e32 v23, -1, v18
	v_pk_add_f32 v[20:21], v[20:21], 0 neg_lo:[1,1] neg_hi:[1,1]
	v_cmp_gt_i32_e64 s[0:1], 0, v18
	v_xor_b32_e32 v22, -1, v19
	s_nop 0
	v_cndmask_b32_e64 v18, v20, v23, s[0:1]
	v_cmp_gt_i32_e64 s[0:1], 0, v19
	s_nop 1
	v_cndmask_b32_e64 v19, v21, v22, s[0:1]
	v_cmp_lt_u32_e64 s[0:1], v175, v139
	s_nop 1
	v_cndmask_b32_e64 v50, 0, v19, s[0:1]
	v_cmp_lt_u32_e64 s[0:1], v178, v139
	s_nop 1
	v_cndmask_b32_e64 v48, 0, v18, s[0:1]
	s_and_saveexec_b64 s[0:1], vcc
	s_xor_b64 s[60:61], exec, s[0:1]
	s_cbranch_execz .LBB0_499
	v_or_b32_e32 v38, 0xa00, v148
	v_min_u32_e32 v26, v38, v0
	v_or_b32_e32 v41, 0xa40, v148
	v_lshl_add_u32 v28, v26, 2, v241
	v_min_u32_e32 v26, v41, v0
	v_or_b32_e32 v98, 0xa80, v148
	v_lshl_add_u32 v29, v26, 2, v241
	v_min_u32_e32 v26, v98, v0
	v_or_b32_e32 v99, 0xac0, v148
	v_lshl_add_u32 v30, v26, 2, v241
	v_min_u32_e32 v26, v99, v0
	v_or_b32_e32 v100, 0xb00, v148
	v_lshl_add_u32 v31, v26, 2, v241
	v_min_u32_e32 v26, v100, v0
	v_or_b32_e32 v101, 0xb40, v148
	v_lshl_add_u32 v32, v26, 2, v241
	v_min_u32_e32 v26, v101, v0
	v_or_b32_e32 v102, 0xb80, v148
	v_lshl_add_u32 v33, v26, 2, v241
	v_min_u32_e32 v26, v102, v0
	v_or_b32_e32 v103, 0xbc0, v148
	v_lshl_add_u32 v34, v26, 2, v241
	v_min_u32_e32 v26, v103, v0
	v_or_b32_e32 v104, 0xc00, v148
	v_lshl_add_u32 v35, v26, 2, v241
	v_min_u32_e32 v26, v104, v0
	v_or_b32_e32 v105, 0xc40, v148
	v_lshl_add_u32 v65, v26, 2, v241
	v_min_u32_e32 v26, v105, v0
	v_or_b32_e32 v106, 0xc80, v148
	v_lshl_add_u32 v66, v26, 2, v241
	v_min_u32_e32 v26, v106, v0
	v_or_b32_e32 v107, 0xcc0, v148
	v_lshl_add_u32 v68, v26, 2, v241
	v_min_u32_e32 v26, v107, v0
	v_or_b32_e32 v108, 0xd00, v148
	v_lshl_add_u32 v70, v26, 2, v241
	v_min_u32_e32 v26, v108, v0
	v_or_b32_e32 v109, 0xd40, v148
	v_lshl_add_u32 v71, v26, 2, v241
	v_min_u32_e32 v26, v109, v0
	v_or_b32_e32 v110, 0xd80, v148
	v_lshl_add_u32 v72, v26, 2, v241
	v_min_u32_e32 v26, v110, v0
	v_or_b32_e32 v111, 0xdc0, v148
	v_lshl_add_u32 v74, v26, 2, v241
	v_min_u32_e32 v26, v111, v0
	v_or_b32_e32 v112, 0xe00, v148
	v_lshl_add_u32 v76, v26, 2, v241
	v_min_u32_e32 v26, v112, v0
	v_lshl_add_u32 v85, v26, 2, v241
	v_min_u32_e32 v26, v201, v0
	v_lshl_add_u32 v90, v26, 2, v241
	v_min_u32_e32 v26, v204, v0
	v_lshl_add_u32 v92, v26, 2, v241
	v_min_u32_e32 v26, v203, v0
	v_lshl_add_u32 v93, v26, 2, v241
	v_min_u32_e32 v26, v206, v0
	v_or_b32_e32 v37, 0x940, v148
	v_or_b32_e32 v39, 0x9c0, v148
	v_lshl_add_u32 v94, v26, 2, v241
	v_min_u32_e32 v26, v205, v0
	v_min_u32_e32 v18, v247, v0
	v_min_u32_e32 v19, v147, v0
	v_min_u32_e32 v20, v146, v0
	v_min_u32_e32 v21, v235, v0
	v_min_u32_e32 v22, v234, v0
	v_min_u32_e32 v23, v37, v0
	v_min_u32_e32 v24, v236, v0
	v_min_u32_e32 v25, v39, v0
	v_lshl_add_u32 v95, v26, 2, v241
	v_min_u32_e32 v26, v208, v0
	v_lshl_add_u32 v18, v18, 2, v241
	v_lshl_add_u32 v19, v19, 2, v241
	v_lshl_add_u32 v20, v20, 2, v241
	v_lshl_add_u32 v21, v21, 2, v241
	v_lshl_add_u32 v22, v22, 2, v241
	v_lshl_add_u32 v23, v23, 2, v241
	v_lshl_add_u32 v24, v24, 2, v241
	v_lshl_add_u32 v25, v25, 2, v241
	v_lshl_add_u32 v96, v26, 2, v241
	v_min_u32_e32 v26, v207, v0
	v_lshl_add_u32 v97, v26, 2, v241
	ds_read_b32 v26, v18
	ds_read_b32 v19, v19
	ds_read_b32 v18, v20
	ds_read_b32 v21, v21
	ds_read_b32 v20, v22
	ds_read_b32 v23, v23
	ds_read_b32 v22, v24
	ds_read_b32 v25, v25
	s_waitcnt lgkmcnt(7)
	v_add_f32_e32 v24, 0, v26
	v_not_b32_e32 v26, v24
	v_or_b32_e32 v27, 0x80000000, v24
	v_cmp_gt_i32_e32 vcc, 0, v24
	s_waitcnt lgkmcnt(5)
	v_pk_add_f32 v[18:19], v[18:19], 0 op_sel_hi:[1,0]
	v_min_u32_e32 v0, v210, v0
	v_cndmask_b32_e32 v24, v27, v26, vcc
	v_cmp_lt_u32_e32 vcc, v247, v139
	v_and_b32_e32 v27, 0x7fffffff, v19
	v_and_b32_e32 v26, 0x7fffffff, v18
	v_cndmask_b32_e32 v91, 0, v24, vcc
	v_xor_b32_e32 v36, -1, v18
	v_pk_add_f32 v[26:27], v[26:27], 0 neg_lo:[1,1] neg_hi:[1,1]
	v_cmp_gt_i32_e32 vcc, 0, v18
	v_xor_b32_e32 v24, -1, v19
	v_lshl_add_u32 v0, v0, 2, v241
	v_cndmask_b32_e32 v18, v26, v36, vcc
	v_cmp_gt_i32_e32 vcc, 0, v19
	s_mov_b32 s11, 0
	s_mov_b32 s34, 31
	v_cndmask_b32_e32 v19, v27, v24, vcc
	v_cmp_lt_u32_e32 vcc, v147, v139
	s_mov_b64 s[20:21], 0
	s_nop 0
	v_cndmask_b32_e32 v49, 0, v19, vcc
	v_cmp_lt_u32_e32 vcc, v146, v139
	s_nop 1
	v_cndmask_b32_e32 v46, 0, v18, vcc
	s_waitcnt lgkmcnt(3)
	v_pk_add_f32 v[18:19], v[20:21], 0 op_sel_hi:[1,0]
	s_nop 0
	v_and_b32_e32 v21, 0x7fffffff, v19
	v_and_b32_e32 v20, 0x7fffffff, v18
	v_xor_b32_e32 v26, -1, v18
	v_pk_add_f32 v[20:21], v[20:21], 0 neg_lo:[1,1] neg_hi:[1,1]
	v_cmp_gt_i32_e32 vcc, 0, v18
	v_xor_b32_e32 v24, -1, v19
	s_nop 0
	v_cndmask_b32_e32 v18, v20, v26, vcc
	v_cmp_gt_i32_e32 vcc, 0, v19
	s_nop 1
	v_cndmask_b32_e32 v19, v21, v24, vcc
	v_cmp_lt_u32_e32 vcc, v235, v139
	s_nop 1
	v_cndmask_b32_e32 v47, 0, v19, vcc
	v_cmp_lt_u32_e32 vcc, v234, v139
	s_nop 1
	v_cndmask_b32_e32 v44, 0, v18, vcc
	s_waitcnt lgkmcnt(1)
	v_pk_add_f32 v[18:19], v[22:23], 0 op_sel_hi:[1,0]
	s_nop 0
	v_and_b32_e32 v21, 0x7fffffff, v19
	v_and_b32_e32 v20, 0x7fffffff, v18
	v_xor_b32_e32 v23, -1, v18
	v_pk_add_f32 v[20:21], v[20:21], 0 neg_lo:[1,1] neg_hi:[1,1]
	v_cmp_gt_i32_e32 vcc, 0, v18
	v_xor_b32_e32 v22, -1, v19
	s_nop 0
	v_cndmask_b32_e32 v18, v20, v23, vcc
	v_cmp_gt_i32_e32 vcc, 0, v19
	s_nop 1
	v_cndmask_b32_e32 v19, v21, v22, vcc
	v_cmp_lt_u32_e32 vcc, v37, v139
	s_nop 1
	v_cndmask_b32_e32 v45, 0, v19, vcc
	v_cmp_lt_u32_e32 vcc, v236, v139
	s_nop 1
	v_cndmask_b32_e32 v42, 0, v18, vcc
	ds_read_b32 v24, v28
	ds_read_b32 v19, v29
	ds_read_b32 v18, v30
	ds_read_b32 v21, v31
	ds_read_b32 v20, v32
	ds_read_b32 v23, v33
	ds_read_b32 v22, v34
	ds_read_b32 v27, v35
	s_waitcnt lgkmcnt(7)
	v_pk_add_f32 v[24:25], v[24:25], 0 op_sel_hi:[1,0]
	s_waitcnt lgkmcnt(5)
	v_pk_add_f32 v[18:19], v[18:19], 0 op_sel_hi:[1,0]
	v_and_b32_e32 v29, 0x7fffffff, v25
	v_and_b32_e32 v28, 0x7fffffff, v24
	v_xor_b32_e32 v30, -1, v24
	v_pk_add_f32 v[28:29], v[28:29], 0 neg_lo:[1,1] neg_hi:[1,1]
	v_cmp_gt_i32_e32 vcc, 0, v24
	v_xor_b32_e32 v26, -1, v25
	s_nop 0
	v_cndmask_b32_e32 v24, v28, v30, vcc
	v_cmp_gt_i32_e32 vcc, 0, v25
	v_xor_b32_e32 v28, -1, v18
	s_nop 0
	v_cndmask_b32_e32 v25, v29, v26, vcc
	v_cmp_lt_u32_e32 vcc, v39, v139
	v_xor_b32_e32 v26, -1, v19
	s_nop 0
	v_cndmask_b32_e32 v43, 0, v25, vcc
	v_cmp_lt_u32_e32 vcc, v38, v139
	v_and_b32_e32 v25, 0x7fffffff, v19
	s_nop 0
	v_cndmask_b32_e32 v40, 0, v24, vcc
	v_and_b32_e32 v24, 0x7fffffff, v18
	v_pk_add_f32 v[24:25], v[24:25], 0 neg_lo:[1,1] neg_hi:[1,1]
	v_cmp_gt_i32_e32 vcc, 0, v18
	s_nop 1
	v_cndmask_b32_e32 v18, v24, v28, vcc
	v_cmp_gt_i32_e32 vcc, 0, v19
	s_nop 1
	v_cndmask_b32_e32 v19, v25, v26, vcc
	v_cmp_lt_u32_e32 vcc, v41, v139
	s_nop 1
	v_cndmask_b32_e32 v41, 0, v19, vcc
	v_cmp_lt_u32_e32 vcc, v98, v139
	s_nop 1
	v_cndmask_b32_e32 v38, 0, v18, vcc
	s_waitcnt lgkmcnt(3)
	v_pk_add_f32 v[18:19], v[20:21], 0 op_sel_hi:[1,0]
	s_nop 0
	v_and_b32_e32 v21, 0x7fffffff, v19
	v_and_b32_e32 v20, 0x7fffffff, v18
	v_xor_b32_e32 v25, -1, v18
	v_pk_add_f32 v[20:21], v[20:21], 0 neg_lo:[1,1] neg_hi:[1,1]
	v_cmp_gt_i32_e32 vcc, 0, v18
	v_xor_b32_e32 v24, -1, v19
	s_nop 0
	v_cndmask_b32_e32 v18, v20, v25, vcc
	v_cmp_gt_i32_e32 vcc, 0, v19
	s_nop 1
	v_cndmask_b32_e32 v19, v21, v24, vcc
	v_cmp_lt_u32_e32 vcc, v99, v139
	s_nop 1
	v_cndmask_b32_e32 v39, 0, v19, vcc
	v_cmp_lt_u32_e32 vcc, v100, v139
	s_nop 1
	v_cndmask_b32_e32 v36, 0, v18, vcc
	s_waitcnt lgkmcnt(1)
	v_pk_add_f32 v[18:19], v[22:23], 0 op_sel_hi:[1,0]
	s_nop 0
	v_and_b32_e32 v21, 0x7fffffff, v19
	v_and_b32_e32 v20, 0x7fffffff, v18
	v_xor_b32_e32 v23, -1, v18
	v_pk_add_f32 v[20:21], v[20:21], 0 neg_lo:[1,1] neg_hi:[1,1]
	v_cmp_gt_i32_e32 vcc, 0, v18
	v_xor_b32_e32 v22, -1, v19
	s_nop 0
	v_cndmask_b32_e32 v18, v20, v23, vcc
	v_cmp_gt_i32_e32 vcc, 0, v19
	s_nop 1
	v_cndmask_b32_e32 v19, v21, v22, vcc
	v_cmp_lt_u32_e32 vcc, v101, v139
	s_nop 1
	v_cndmask_b32_e32 v37, 0, v19, vcc
	v_cmp_lt_u32_e32 vcc, v102, v139
	s_nop 1
	v_cndmask_b32_e32 v34, 0, v18, vcc
	ds_read_b32 v26, v65
	ds_read_b32 v19, v66
	ds_read_b32 v18, v68
	ds_read_b32 v21, v70
	ds_read_b32 v20, v71
	ds_read_b32 v23, v72
	ds_read_b32 v22, v74
	ds_read_b32 v25, v76
	s_waitcnt lgkmcnt(7)
	v_pk_add_f32 v[26:27], v[26:27], 0 op_sel_hi:[1,0]
	s_waitcnt lgkmcnt(5)
	v_pk_add_f32 v[18:19], v[18:19], 0 op_sel_hi:[1,0]
	v_and_b32_e32 v29, 0x7fffffff, v27
	v_and_b32_e32 v28, 0x7fffffff, v26
	v_xor_b32_e32 v30, -1, v26
	v_pk_add_f32 v[28:29], v[28:29], 0 neg_lo:[1,1] neg_hi:[1,1]
	v_cmp_gt_i32_e32 vcc, 0, v26
	v_xor_b32_e32 v24, -1, v27
	s_nop 0
	v_cndmask_b32_e32 v26, v28, v30, vcc
	v_cmp_gt_i32_e32 vcc, 0, v27
	v_and_b32_e32 v27, 0x7fffffff, v19
	v_xor_b32_e32 v28, -1, v18
	v_cndmask_b32_e32 v24, v29, v24, vcc
	v_cmp_lt_u32_e32 vcc, v103, v139
	s_nop 1
	v_cndmask_b32_e32 v35, 0, v24, vcc
	v_cmp_lt_u32_e32 vcc, v104, v139
	v_xor_b32_e32 v24, -1, v19
	s_nop 0
	v_cndmask_b32_e32 v32, 0, v26, vcc
	v_and_b32_e32 v26, 0x7fffffff, v18
	v_pk_add_f32 v[26:27], v[26:27], 0 neg_lo:[1,1] neg_hi:[1,1]
	v_cmp_gt_i32_e32 vcc, 0, v18
	s_nop 1
	v_cndmask_b32_e32 v18, v26, v28, vcc
	v_cmp_gt_i32_e32 vcc, 0, v19
	s_nop 1
	v_cndmask_b32_e32 v19, v27, v24, vcc
	v_cmp_lt_u32_e32 vcc, v105, v139
	s_nop 1
	v_cndmask_b32_e32 v33, 0, v19, vcc
	v_cmp_lt_u32_e32 vcc, v106, v139
	s_nop 1
	v_cndmask_b32_e32 v30, 0, v18, vcc
	s_waitcnt lgkmcnt(3)
	v_pk_add_f32 v[18:19], v[20:21], 0 op_sel_hi:[1,0]
	s_nop 0
	v_and_b32_e32 v21, 0x7fffffff, v19
	v_and_b32_e32 v20, 0x7fffffff, v18
	v_xor_b32_e32 v26, -1, v18
	v_pk_add_f32 v[20:21], v[20:21], 0 neg_lo:[1,1] neg_hi:[1,1]
	v_cmp_gt_i32_e32 vcc, 0, v18
	v_xor_b32_e32 v24, -1, v19
	s_nop 0
	v_cndmask_b32_e32 v18, v20, v26, vcc
	v_cmp_gt_i32_e32 vcc, 0, v19
	s_nop 1
	v_cndmask_b32_e32 v19, v21, v24, vcc
	v_cmp_lt_u32_e32 vcc, v107, v139
	s_nop 1
	v_cndmask_b32_e32 v31, 0, v19, vcc
	v_cmp_lt_u32_e32 vcc, v108, v139
	s_nop 1
	v_cndmask_b32_e32 v28, 0, v18, vcc
	s_waitcnt lgkmcnt(1)
	v_pk_add_f32 v[18:19], v[22:23], 0 op_sel_hi:[1,0]
	s_nop 0
	v_and_b32_e32 v21, 0x7fffffff, v19
	v_and_b32_e32 v20, 0x7fffffff, v18
	v_xor_b32_e32 v23, -1, v18
	v_pk_add_f32 v[20:21], v[20:21], 0 neg_lo:[1,1] neg_hi:[1,1]
	v_cmp_gt_i32_e32 vcc, 0, v18
	v_xor_b32_e32 v22, -1, v19
	s_nop 0
	v_cndmask_b32_e32 v18, v20, v23, vcc
	v_cmp_gt_i32_e32 vcc, 0, v19
	s_nop 1
	v_cndmask_b32_e32 v19, v21, v22, vcc
	v_cmp_lt_u32_e32 vcc, v109, v139
	s_nop 1
	v_cndmask_b32_e32 v29, 0, v19, vcc
	v_cmp_lt_u32_e32 vcc, v110, v139
	s_nop 1
	v_cndmask_b32_e32 v26, 0, v18, vcc
	ds_read_b32 v24, v85
	ds_read_b32 v19, v90
	ds_read_b32 v18, v92
	ds_read_b32 v21, v93
	ds_read_b32 v20, v94
	ds_read_b32 v71, v95
	ds_read_b32 v70, v96
	ds_read_b32 v93, v97
	s_waitcnt lgkmcnt(7)
	v_pk_add_f32 v[22:23], v[24:25], 0 op_sel_hi:[1,0]
	s_waitcnt lgkmcnt(5)
	v_pk_add_f32 v[18:19], v[18:19], 0 op_sel_hi:[1,0]
	v_and_b32_e32 v25, 0x7fffffff, v23
	v_and_b32_e32 v24, 0x7fffffff, v22
	v_xor_b32_e32 v65, -1, v22
	v_pk_add_f32 v[24:25], v[24:25], 0 neg_lo:[1,1] neg_hi:[1,1]
	v_cmp_gt_i32_e32 vcc, 0, v22
	v_xor_b32_e32 v27, -1, v23
	ds_read_b32 v92, v0
	v_cndmask_b32_e32 v22, v24, v65, vcc
	v_cmp_gt_i32_e32 vcc, 0, v23
	v_xor_b32_e32 v65, -1, v18
	s_nop 0
	v_cndmask_b32_e32 v23, v25, v27, vcc
	v_cmp_lt_u32_e32 vcc, v111, v139
	v_xor_b32_e32 v25, -1, v19
	s_nop 0
	v_cndmask_b32_e32 v27, 0, v23, vcc
	v_cmp_lt_u32_e32 vcc, v112, v139
	v_and_b32_e32 v23, 0x7fffffff, v19
	s_nop 0
	v_cndmask_b32_e32 v24, 0, v22, vcc
	v_and_b32_e32 v22, 0x7fffffff, v18
	v_pk_add_f32 v[22:23], v[22:23], 0 neg_lo:[1,1] neg_hi:[1,1]
	v_cmp_gt_i32_e32 vcc, 0, v18
	s_nop 1
	v_cndmask_b32_e32 v18, v22, v65, vcc
	v_cmp_gt_i32_e32 vcc, 0, v19
	s_nop 1
	v_cndmask_b32_e32 v19, v23, v25, vcc
	v_cmp_lt_u32_e32 vcc, v201, v139
	s_nop 1
	v_cndmask_b32_e32 v25, 0, v19, vcc
	v_cmp_lt_u32_e32 vcc, v204, v139
	s_nop 1
	v_cndmask_b32_e32 v22, 0, v18, vcc
	s_waitcnt lgkmcnt(4)
	v_pk_add_f32 v[18:19], v[20:21], 0 op_sel_hi:[1,0]
	s_nop 0
	v_and_b32_e32 v21, 0x7fffffff, v19
	v_and_b32_e32 v20, 0x7fffffff, v18
	v_xor_b32_e32 v65, -1, v18
	v_pk_add_f32 v[20:21], v[20:21], 0 neg_lo:[1,1] neg_hi:[1,1]
	v_cmp_gt_i32_e32 vcc, 0, v18
	v_xor_b32_e32 v23, -1, v19
	s_nop 0
	v_cndmask_b32_e32 v18, v20, v65, vcc
	v_cmp_gt_i32_e32 vcc, 0, v19
	s_nop 1
	v_cndmask_b32_e32 v19, v21, v23, vcc
	v_cmp_lt_u32_e32 vcc, v203, v139
	s_nop 1
	v_cndmask_b32_e32 v23, 0, v19, vcc
	v_cmp_lt_u32_e32 vcc, v206, v139
	s_nop 1
	v_cndmask_b32_e32 v20, 0, v18, vcc
	s_waitcnt lgkmcnt(2)
	v_pk_add_f32 v[18:19], v[70:71], 0 op_sel_hi:[1,0]
	s_nop 0
	v_and_b32_e32 v71, 0x7fffffff, v19
	v_and_b32_e32 v70, 0x7fffffff, v18
	v_xor_b32_e32 v65, -1, v18
	v_pk_add_f32 v[70:71], v[70:71], 0 neg_lo:[1,1] neg_hi:[1,1]
	v_cmp_gt_i32_e32 vcc, 0, v18
	v_xor_b32_e32 v21, -1, v19
	s_nop 0
	v_cndmask_b32_e32 v18, v70, v65, vcc
	v_cmp_gt_i32_e32 vcc, 0, v19
	s_nop 1
	v_cndmask_b32_e32 v19, v71, v21, vcc
	v_cmp_lt_u32_e32 vcc, v205, v139
	s_waitcnt lgkmcnt(0)
	v_pk_add_f32 v[70:71], v[92:93], 0 op_sel_hi:[1,0]
	v_cndmask_b32_e32 v21, 0, v19, vcc
	v_cmp_lt_u32_e32 vcc, v208, v139
	v_and_b32_e32 v93, 0x7fffffff, v71
	v_and_b32_e32 v92, 0x7fffffff, v70
	v_cndmask_b32_e32 v18, 0, v18, vcc
	v_xor_b32_e32 v19, -1, v70
	v_pk_add_f32 v[92:93], v[92:93], 0 neg_lo:[1,1] neg_hi:[1,1]
	v_cmp_gt_i32_e32 vcc, 0, v70
	v_xor_b32_e32 v0, -1, v71
	s_nop 0
	v_cndmask_b32_e32 v65, v92, v19, vcc
	v_cmp_gt_i32_e32 vcc, 0, v71
	s_nop 1
	v_cndmask_b32_e32 v0, v93, v0, vcc
	v_cmp_lt_u32_e32 vcc, v207, v139
	s_nop 1
	v_cndmask_b32_e32 v19, 0, v0, vcc
	v_cmp_lt_u32_e32 vcc, v210, v139
	s_nop 1
	v_cndmask_b32_e32 v0, 0, v65, vcc
	s_branch .LBB0_360

.LBB0_363:
	s_lshl_b32 s2, 1, s34
	s_or_b32 s2, s2, s11
	s_mov_b32 s3, 0
	v_cmp_le_u32_e64 s[42:43], s2, v67
	v_cmp_le_u32_e64 s[44:45], s2, v62
	v_cmp_le_u32_e64 s[46:47], s2, v89
	v_cmp_le_u32_e64 s[48:49], s2, v88
	v_cmp_le_u32_e64 s[50:51], s2, v87
	v_cmp_le_u32_e64 s[52:53], s2, v86
	v_cmp_le_u32_e64 s[54:55], s2, v84
	v_cmp_le_u32_e64 s[56:57], s2, v83
	s_bcnt1_i32_b64 s62, s[42:43]
	s_bcnt1_i32_b64 s63, s[44:45]
	s_bcnt1_i32_b64 s64, s[46:47]
	s_bcnt1_i32_b64 s65, s[48:49]
	s_add_i32 s3, s3, s62
	s_add_i32 s3, s3, s63
	s_add_i32 s3, s3, s64
	s_add_i32 s3, s3, s65
	v_cmp_le_u32_e64 s[42:43], s2, v82
	v_cmp_le_u32_e64 s[44:45], s2, v81
	v_cmp_le_u32_e64 s[46:47], s2, v80
	v_cmp_le_u32_e64 s[48:49], s2, v79
	s_bcnt1_i32_b64 s62, s[50:51]
	s_bcnt1_i32_b64 s63, s[52:53]
	s_bcnt1_i32_b64 s64, s[54:55]
	s_bcnt1_i32_b64 s65, s[56:57]
	s_add_i32 s3, s3, s62
	s_add_i32 s3, s3, s63
	s_add_i32 s3, s3, s64
	s_add_i32 s3, s3, s65
	v_cmp_le_u32_e64 s[50:51], s2, v78
	v_cmp_le_u32_e64 s[52:53], s2, v77
	v_cmp_le_u32_e64 s[54:55], s2, v75
	v_cmp_le_u32_e64 s[56:57], s2, v73
	s_bcnt1_i32_b64 s62, s[42:43]
	s_bcnt1_i32_b64 s63, s[44:45]
	s_bcnt1_i32_b64 s64, s[46:47]
	s_bcnt1_i32_b64 s65, s[48:49]
	s_add_i32 s3, s3, s62
	s_add_i32 s3, s3, s63
	s_add_i32 s3, s3, s64
	s_add_i32 s3, s3, s65
	v_cmp_le_u32_e64 s[42:43], s2, v69
	v_cmp_le_u32_e64 s[44:45], s2, v64
	v_cmp_le_u32_e64 s[46:47], s2, v63
	v_cmp_le_u32_e64 s[48:49], s2, v61
	s_bcnt1_i32_b64 s62, s[50:51]
	s_bcnt1_i32_b64 s63, s[52:53]
	s_bcnt1_i32_b64 s64, s[54:55]
	s_bcnt1_i32_b64 s65, s[56:57]
	s_add_i32 s3, s3, s62
	s_add_i32 s3, s3, s63
	s_add_i32 s3, s3, s64
	s_add_i32 s3, s3, s65
	v_cmp_le_u32_e64 s[50:51], s2, v60
	v_cmp_le_u32_e64 s[52:53], s2, v59
	v_cmp_le_u32_e64 s[54:55], s2, v58
	v_cmp_le_u32_e64 s[56:57], s2, v57
	s_bcnt1_i32_b64 s62, s[42:43]
	s_bcnt1_i32_b64 s63, s[44:45]
	s_bcnt1_i32_b64 s64, s[46:47]
	s_bcnt1_i32_b64 s65, s[48:49]
	s_add_i32 s3, s3, s62
	s_add_i32 s3, s3, s63
	s_add_i32 s3, s3, s64
	s_add_i32 s3, s3, s65
	v_cmp_le_u32_e64 s[42:43], s2, v56
	v_cmp_le_u32_e64 s[44:45], s2, v55
	v_cmp_le_u32_e64 s[46:47], s2, v54
	v_cmp_le_u32_e64 s[48:49], s2, v53
	s_bcnt1_i32_b64 s62, s[50:51]
	s_bcnt1_i32_b64 s63, s[52:53]
	s_bcnt1_i32_b64 s64, s[54:55]
	s_bcnt1_i32_b64 s65, s[56:57]
	s_add_i32 s3, s3, s62
	s_add_i32 s3, s3, s63
	s_add_i32 s3, s3, s64
	s_add_i32 s3, s3, s65
	v_cmp_le_u32_e64 s[50:51], s2, v52
	v_cmp_le_u32_e64 s[52:53], s2, v51
	v_cmp_le_u32_e64 s[54:55], s2, v50
	v_cmp_le_u32_e64 s[56:57], s2, v48
	s_bcnt1_i32_b64 s62, s[42:43]
	s_bcnt1_i32_b64 s63, s[44:45]
	s_bcnt1_i32_b64 s64, s[46:47]
	s_bcnt1_i32_b64 s65, s[48:49]
	s_add_i32 s3, s3, s62
	s_add_i32 s3, s3, s63
	s_add_i32 s3, s3, s64
	s_add_i32 s3, s3, s65
	v_cmp_le_u32_e64 s[42:43], s2, v91
	v_cmp_le_u32_e64 s[44:45], s2, v49
	v_cmp_le_u32_e64 s[46:47], s2, v46
	v_cmp_le_u32_e64 s[48:49], s2, v47
	s_bcnt1_i32_b64 s62, s[50:51]
	s_bcnt1_i32_b64 s63, s[52:53]
	s_bcnt1_i32_b64 s64, s[54:55]
	s_bcnt1_i32_b64 s65, s[56:57]
	s_add_i32 s3, s3, s62
	s_add_i32 s3, s3, s63
	s_add_i32 s3, s3, s64
	s_add_i32 s3, s3, s65
	v_cmp_le_u32_e64 s[50:51], s2, v44
	v_cmp_le_u32_e64 s[52:53], s2, v45
	v_cmp_le_u32_e64 s[54:55], s2, v42
	v_cmp_le_u32_e64 s[56:57], s2, v43
	s_bcnt1_i32_b64 s62, s[42:43]
	s_bcnt1_i32_b64 s63, s[44:45]
	s_bcnt1_i32_b64 s64, s[46:47]
	s_bcnt1_i32_b64 s65, s[48:49]
	s_add_i32 s3, s3, s62
	s_add_i32 s3, s3, s63
	s_add_i32 s3, s3, s64
	s_add_i32 s3, s3, s65
	v_cmp_le_u32_e64 s[42:43], s2, v40
	v_cmp_le_u32_e64 s[44:45], s2, v41
	v_cmp_le_u32_e64 s[46:47], s2, v38
	v_cmp_le_u32_e64 s[48:49], s2, v39
	s_bcnt1_i32_b64 s62, s[50:51]
	s_bcnt1_i32_b64 s63, s[52:53]
	s_bcnt1_i32_b64 s64, s[54:55]
	s_bcnt1_i32_b64 s65, s[56:57]
	s_add_i32 s3, s3, s62
	s_add_i32 s3, s3, s63
	s_add_i32 s3, s3, s64
	s_add_i32 s3, s3, s65
	v_cmp_le_u32_e64 s[50:51], s2, v36
	v_cmp_le_u32_e64 s[52:53], s2, v37
	v_cmp_le_u32_e64 s[54:55], s2, v34
	v_cmp_le_u32_e64 s[56:57], s2, v35
	s_bcnt1_i32_b64 s62, s[42:43]
	s_bcnt1_i32_b64 s63, s[44:45]
	s_bcnt1_i32_b64 s64, s[46:47]
	s_bcnt1_i32_b64 s65, s[48:49]
	s_add_i32 s3, s3, s62
	s_add_i32 s3, s3, s63
	s_add_i32 s3, s3, s64
	s_add_i32 s3, s3, s65
	v_cmp_le_u32_e64 s[42:43], s2, v32
	v_cmp_le_u32_e64 s[44:45], s2, v33
	v_cmp_le_u32_e64 s[46:47], s2, v30
	v_cmp_le_u32_e64 s[48:49], s2, v31
	s_bcnt1_i32_b64 s62, s[50:51]
	s_bcnt1_i32_b64 s63, s[52:53]
	s_bcnt1_i32_b64 s64, s[54:55]
	s_bcnt1_i32_b64 s65, s[56:57]
	s_add_i32 s3, s3, s62
	s_add_i32 s3, s3, s63
	s_add_i32 s3, s3, s64
	s_add_i32 s3, s3, s65
	v_cmp_le_u32_e64 s[50:51], s2, v28
	v_cmp_le_u32_e64 s[52:53], s2, v29
	v_cmp_le_u32_e64 s[54:55], s2, v26
	v_cmp_le_u32_e64 s[56:57], s2, v27
	s_bcnt1_i32_b64 s62, s[42:43]
	s_bcnt1_i32_b64 s63, s[44:45]
	s_bcnt1_i32_b64 s64, s[46:47]
	s_bcnt1_i32_b64 s65, s[48:49]
	s_add_i32 s3, s3, s62
	s_add_i32 s3, s3, s63
	s_add_i32 s3, s3, s64
	s_add_i32 s3, s3, s65
	v_cmp_le_u32_e64 s[42:43], s2, v24
	v_cmp_le_u32_e64 s[44:45], s2, v25
	v_cmp_le_u32_e64 s[46:47], s2, v22
	v_cmp_le_u32_e64 s[48:49], s2, v23
	s_bcnt1_i32_b64 s62, s[50:51]
	s_bcnt1_i32_b64 s63, s[52:53]
	s_bcnt1_i32_b64 s64, s[54:55]
	s_bcnt1_i32_b64 s65, s[56:57]
	s_add_i32 s3, s3, s62
	s_add_i32 s3, s3, s63
	s_add_i32 s3, s3, s64
	s_add_i32 s3, s3, s65
	v_cmp_le_u32_e64 s[50:51], s2, v20
	v_cmp_le_u32_e64 s[52:53], s2, v21
	v_cmp_le_u32_e64 s[54:55], s2, v18
	v_cmp_le_u32_e64 s[56:57], s2, v19
	s_bcnt1_i32_b64 s62, s[42:43]
	s_bcnt1_i32_b64 s63, s[44:45]
	s_bcnt1_i32_b64 s64, s[46:47]
	s_bcnt1_i32_b64 s65, s[48:49]
	s_add_i32 s3, s3, s62
	s_add_i32 s3, s3, s63
	s_add_i32 s3, s3, s64
	s_add_i32 s3, s3, s65
	v_cmp_le_u32_e64 s[42:43], s2, v0
	s_bcnt1_i32_b64 s62, s[50:51]
	s_bcnt1_i32_b64 s63, s[52:53]
	s_bcnt1_i32_b64 s64, s[54:55]
	s_bcnt1_i32_b64 s65, s[56:57]
	s_add_i32 s3, s3, s62
	s_add_i32 s3, s3, s63
	s_add_i32 s3, s3, s64
	s_add_i32 s3, s3, s65
	s_bcnt1_i32_b64 s62, s[42:43]
	s_add_i32 s3, s3, s62
	s_cmpk_gt_i32 s3, 0xff
	s_cselect_b32 s36, s2, s11
	s_cmpk_eq_i32 s3, 0x100
	s_cselect_b64 s[2:3], -1, 0
	v_sub_co_u32_e64 v76, s[22:23], s34, 1
	s_or_b64 s[2:3], s[22:23], s[2:3]
	v_readfirstlane_b32 s34, v76
	s_andn2_b64 s[30:31], s[30:31], exec
	s_orn2_b64 s[2:3], s[2:3], exec
	s_branch .LBB0_359

.LBB0_505:
	s_lshl_b32 s2, 1, s11
	s_or_b32 s2, s2, s40
	s_mov_b32 s3, 0
	v_cmp_le_u32_e64 s[42:43], s2, v67
	v_cmp_le_u32_e64 s[44:45], s2, v62
	v_cmp_le_u32_e64 s[46:47], s2, v89
	v_cmp_le_u32_e64 s[48:49], s2, v88
	v_cmp_le_u32_e64 s[50:51], s2, v87
	v_cmp_le_u32_e64 s[52:53], s2, v86
	v_cmp_le_u32_e64 s[54:55], s2, v84
	v_cmp_le_u32_e64 s[56:57], s2, v83
	s_bcnt1_i32_b64 s62, s[42:43]
	s_bcnt1_i32_b64 s63, s[44:45]
	s_bcnt1_i32_b64 s64, s[46:47]
	s_bcnt1_i32_b64 s65, s[48:49]
	s_add_i32 s3, s3, s62
	s_add_i32 s3, s3, s63
	s_add_i32 s3, s3, s64
	s_add_i32 s3, s3, s65
	v_cmp_le_u32_e64 s[42:43], s2, v82
	v_cmp_le_u32_e64 s[44:45], s2, v81
	v_cmp_le_u32_e64 s[46:47], s2, v80
	v_cmp_le_u32_e64 s[48:49], s2, v79
	s_bcnt1_i32_b64 s62, s[50:51]
	s_bcnt1_i32_b64 s63, s[52:53]
	s_bcnt1_i32_b64 s64, s[54:55]
	s_bcnt1_i32_b64 s65, s[56:57]
	s_add_i32 s3, s3, s62
	s_add_i32 s3, s3, s63
	s_add_i32 s3, s3, s64
	s_add_i32 s3, s3, s65
	v_cmp_le_u32_e64 s[50:51], s2, v78
	v_cmp_le_u32_e64 s[52:53], s2, v77
	v_cmp_le_u32_e64 s[54:55], s2, v75
	v_cmp_le_u32_e64 s[56:57], s2, v73
	s_bcnt1_i32_b64 s62, s[42:43]
	s_bcnt1_i32_b64 s63, s[44:45]
	s_bcnt1_i32_b64 s64, s[46:47]
	s_bcnt1_i32_b64 s65, s[48:49]
	s_add_i32 s3, s3, s62
	s_add_i32 s3, s3, s63
	s_add_i32 s3, s3, s64
	s_add_i32 s3, s3, s65
	v_cmp_le_u32_e64 s[42:43], s2, v69
	v_cmp_le_u32_e64 s[44:45], s2, v64
	v_cmp_le_u32_e64 s[46:47], s2, v63
	v_cmp_le_u32_e64 s[48:49], s2, v61
	s_bcnt1_i32_b64 s62, s[50:51]
	s_bcnt1_i32_b64 s63, s[52:53]
	s_bcnt1_i32_b64 s64, s[54:55]
	s_bcnt1_i32_b64 s65, s[56:57]
	s_add_i32 s3, s3, s62
	s_add_i32 s3, s3, s63
	s_add_i32 s3, s3, s64
	s_add_i32 s3, s3, s65
	v_cmp_le_u32_e64 s[50:51], s2, v60
	v_cmp_le_u32_e64 s[52:53], s2, v59
	v_cmp_le_u32_e64 s[54:55], s2, v58
	v_cmp_le_u32_e64 s[56:57], s2, v57
	s_bcnt1_i32_b64 s62, s[42:43]
	s_bcnt1_i32_b64 s63, s[44:45]
	s_bcnt1_i32_b64 s64, s[46:47]
	s_bcnt1_i32_b64 s65, s[48:49]
	s_add_i32 s3, s3, s62
	s_add_i32 s3, s3, s63
	s_add_i32 s3, s3, s64
	s_add_i32 s3, s3, s65
	v_cmp_le_u32_e64 s[42:43], s2, v56
	v_cmp_le_u32_e64 s[44:45], s2, v55
	v_cmp_le_u32_e64 s[46:47], s2, v54
	v_cmp_le_u32_e64 s[48:49], s2, v53
	s_bcnt1_i32_b64 s62, s[50:51]
	s_bcnt1_i32_b64 s63, s[52:53]
	s_bcnt1_i32_b64 s64, s[54:55]
	s_bcnt1_i32_b64 s65, s[56:57]
	s_add_i32 s3, s3, s62
	s_add_i32 s3, s3, s63
	s_add_i32 s3, s3, s64
	s_add_i32 s3, s3, s65
	v_cmp_le_u32_e64 s[50:51], s2, v52
	v_cmp_le_u32_e64 s[52:53], s2, v51
	v_cmp_le_u32_e64 s[54:55], s2, v50
	v_cmp_le_u32_e64 s[56:57], s2, v48
	s_bcnt1_i32_b64 s62, s[42:43]
	s_bcnt1_i32_b64 s63, s[44:45]
	s_bcnt1_i32_b64 s64, s[46:47]
	s_bcnt1_i32_b64 s65, s[48:49]
	s_add_i32 s3, s3, s62
	s_add_i32 s3, s3, s63
	s_add_i32 s3, s3, s64
	s_add_i32 s3, s3, s65
	s_bcnt1_i32_b64 s62, s[50:51]
	s_bcnt1_i32_b64 s63, s[52:53]
	s_bcnt1_i32_b64 s64, s[54:55]
	s_bcnt1_i32_b64 s65, s[56:57]
	s_add_i32 s3, s3, s62
	s_add_i32 s3, s3, s63
	s_add_i32 s3, s3, s64
	s_add_i32 s3, s3, s65
	s_cmpk_gt_u32 s3, 0xff
	s_cselect_b32 s28, s2, s40
	s_cmpk_eq_i32 s3, 0x100
	s_cselect_b64 s[2:3], -1, 0
	v_sub_co_u32_e64 v24, s[26:27], s11, 1
	s_or_b64 s[2:3], s[26:27], s[2:3]
	v_readfirstlane_b32 s11, v24
	s_andn2_b64 s[36:37], s[36:37], exec
	s_orn2_b64 s[2:3], s[2:3], exec
	s_branch .LBB0_501

.LBB0_765:
	s_or_b64 exec, exec, s[8:9]
	v_mov_b32_e32 v215, 0x3727c5ac
	v_readlane_b32 s2, v252, 61
	v_readlane_b32 s16, v252, 38
	s_mul_i32 s1, s2, 0x6000
	v_readlane_b32 s18, v252, 40
	v_readlane_b32 s20, v252, 42
	v_readlane_b32 s36, v251, 1
	v_readlane_b32 s3, v252, 62
	s_mul_hi_i32 s0, s2, 0x6000
	v_readlane_b32 s19, v252, 41
	v_readlane_b32 s21, v252, 43
	v_readlane_b32 s22, v252, 44
	v_readlane_b32 s23, v252, 45
	s_add_u32 s20, s18, s1
	v_readlane_b32 s50, v251, 15
	v_readlane_b32 s51, v251, 16
	v_readlane_b32 s24, v252, 46
	s_addc_u32 s21, s19, s0
	s_lshl_b64 s[22:23], s[2:3], 5
	s_lshl_b32 s0, s2, 2
	s_mov_b64 s[2:3], s[50:51]
	v_readlane_b32 s25, v252, 47
	s_barrier
	s_add_u32 s24, s2, 0xa180000
	s_addc_u32 s25, s3, 0
	v_writelane_b32 v253, s0, 60
	s_add_u32 s0, s2, 0x23d92200
	v_readlane_b32 s28, v252, 50
	s_addc_u32 s1, s3, 0
	v_readlane_b32 s29, v252, 51
	s_add_u32 s28, s2, 0x20880000
	v_writelane_b32 v253, s0, 54
	s_addc_u32 s29, s3, 0
	v_readlane_b32 s26, v252, 48
	v_writelane_b32 v253, s1, 55
	s_add_u32 s0, s2, 0x21980000
	s_addc_u32 s1, s3, 0
	v_writelane_b32 v253, s0, 56
	s_waitcnt vmcnt(0)
	v_mov_b32_e32 v4, v211
	v_readlane_b32 s27, v252, 49
	v_writelane_b32 v253, s1, 57
	v_and_b32_e32 v118, 63, v4
	v_readlane_b32 s0, v253, 26
	v_readlane_b32 s1, v253, 27
	s_add_u32 s0, s2, s0
	s_addc_u32 s1, s3, s1
	s_add_u32 s26, s0, 0x23f9a204
	s_movk_i32 s0, 0x17f
	v_cmp_lt_i32_e64 s[88:89], s0, v4
	s_movk_i32 s0, 0x1bf
	v_cmp_lt_u32_e64 s[8:9], s0, v4
	v_lshlrev_b32_e32 v18, 2, v118
	v_readlane_b32 s0, v252, 29
	s_addc_u32 s27, s1, 0
	v_mov_b32_e32 v19, v1
	v_add_u32_e32 v121, s0, v18
	v_cmp_eq_u32_e64 s[0:1], 63, v118
	v_ashrrev_i32_e32 v0, 6, v4
	v_cmp_lt_i32_e32 vcc, 2, v0
	v_writelane_b32 v253, s0, 40
	v_lshlrev_b32_e32 v124, 3, v0
	v_cmp_lt_i32_e64 s[52:53], 5, v0
	v_writelane_b32 v253, s1, 41
	s_mov_b32 s0, 0x2aaaaaab
	v_mul_hi_i32 v2, v4, s0
	v_lshrrev_b32_e32 v3, 31, v2
	v_ashrrev_i32_e32 v2, 5, v2
	v_add_u32_e32 v15, v2, v3
	s_movk_i32 s0, 0xff40
	v_mad_u64_u32 v[2:3], s[0:1], v15, s0, v[4:5]
	v_lshlrev_b32_e32 v3, 1, v2
	v_lshlrev_b32_e32 v2, 3, v2
	v_and_b32_e32 v3, 0x7e, v3
	s_movk_i32 s0, 0xfe00
	v_and_or_b32 v122, v2, s0, v3
	v_lshl_add_u64 v[2:3], s[2:3], 0, v[18:19]
	s_mov_b64 s[0:1], 0x1c600000
	v_lshl_add_u64 v[20:21], v[2:3], 0, s[0:1]
	v_add_u32_e32 v2, -3, v0
	v_cmp_ne_u32_e64 s[12:13], 6, v0
	v_cmp_gt_i32_e64 s[18:19], 3, v0
	v_cndmask_b32_e32 v0, v0, v2, vcc
	v_cmp_eq_u32_e64 s[0:1], 0, v0
	v_readlane_b32 s17, v252, 39
	v_mov_b32_e32 v7, 0x100
	v_cndmask_b32_e64 v6, 32, 0, s[0:1]
	s_movk_i32 s0, 0x100
	v_and_b32_e32 v17, 31, v4
	v_cndmask_b32_e64 v7, v7, 0, vcc
	v_cmp_eq_u32_e32 vcc, 2, v0
	v_cmp_gt_i32_e64 s[16:17], s0, v4
	s_movk_i32 s0, 0x80
	v_or_b32_e32 v3, v6, v17
	v_cndmask_b32_e64 v0, 0, 32, vcc
	v_cmp_gt_i32_e32 vcc, s0, v4
	v_cmp_eq_u32_e64 s[0:1], 0, v118
	v_mul_u32_u24_e32 v3, 0x610, v3
	v_add3_u32 v7, 0, v3, v7
	v_writelane_b32 v253, s0, 36
	v_or_b32_e32 v3, v0, v17
	v_bfe_u32 v2, v4, 5, 1
	v_writelane_b32 v253, s1, 37
	v_cmp_gt_u32_e64 s[0:1], 2, v118
	v_lshlrev_b32_e32 v0, 1, v3
	v_lshl_or_b32 v28, v2, 2, v6
	v_writelane_b32 v253, s0, 30
	v_lshl_add_u64 v[22:23], s[28:29], 0, v[0:1]
	v_add_u32_e32 v0, 0x100, v4
	v_writelane_b32 v253, s1, 31
	v_cmp_gt_u32_e64 s[0:1], 4, v118
	v_cndmask_b32_e32 v0, v4, v0, vcc
	v_or_b32_e32 v41, 10, v28
	v_writelane_b32 v253, s0, 32
	v_readlane_b32 s11, v252, 27
	v_readlane_b32 s34, v252, 28
	v_lshlrev_b32_e32 v125, 2, v0
	v_mov_b32_e32 v0, 0x1f80000
	v_bfrev_b32_e32 v8, 32
	v_writelane_b32 v253, s1, 33
	v_cmp_gt_u32_e64 s[0:1], 8, v118
	v_lshlrev_b32_e32 v30, 2, v41
	v_or_b32_e32 v43, 11, v28
	v_cndmask_b32_e32 v0, v0, v8, vcc
	v_writelane_b32 v253, s0, 34
	v_add_u32_e32 v141, s11, v30
	v_add_u32_e32 v142, s34, v30
	v_lshlrev_b32_e32 v30, 2, v43
	v_or_b32_e32 v45, 16, v28
	v_lshl_add_u64 v[24:25], s[2:3], 0, v[0:1]
	v_writelane_b32 v253, s1, 35
	v_cmp_gt_u32_e64 s[0:1], 16, v118
	v_lshlrev_b32_e32 v0, 7, v17
	v_add_u32_e32 v143, s11, v30
	v_add_u32_e32 v144, s34, v30
	v_lshlrev_b32_e32 v30, 2, v45
	v_or_b32_e32 v47, 17, v28
	v_writelane_b32 v253, s0, 38
	v_lshl_add_u64 v[26:27], s[28:29], 0, v[0:1]
	v_and_b32_e32 v0, 7, v4
	v_add_u32_e32 v145, s11, v30
	v_add_u32_e32 v148, s34, v30
	v_lshlrev_b32_e32 v30, 2, v47
	v_or_b32_e32 v49, 18, v28
	v_writelane_b32 v253, s1, 39
	v_cmp_gt_u32_e64 s[0:1], 32, v118
	v_bfe_u32 v29, v4, 3, 3
	v_lshlrev_b32_e32 v0, 4, v0
	v_add_u32_e32 v149, s11, v30
	v_add_u32_e32 v150, s34, v30
	v_lshlrev_b32_e32 v30, 2, v49
	v_or_b32_e32 v51, 19, v28
	v_readlane_b32 s30, v252, 52
	v_readlane_b32 s31, v252, 53
	v_writelane_b32 v253, s0, 42
	v_lshl_or_b32 v0, v29, 7, v0
	v_add_u32_e32 v151, s11, v30
	v_add_u32_e32 v152, s34, v30
	v_lshlrev_b32_e32 v30, 2, v51
	v_or_b32_e32 v53, 24, v28
	v_or_b32_e32 v59, 27, v28
	v_writelane_b32 v253, s1, 43
	v_cmp_le_u32_e64 s[30:31], v3, v28
	v_lshlrev_b32_e32 v8, 2, v28
	v_lshl_add_u64 v[12:13], s[2:3], 0, v[0:1]
	v_cmp_lt_u32_e64 s[0:1], v3, v28
	v_lshlrev_b32_e32 v0, 6, v28
	v_or_b32_e32 v31, 1, v28
	v_or_b32_e32 v33, 2, v28
	v_or_b32_e32 v35, 3, v28
	v_or_b32_e32 v37, 8, v28
	v_or_b32_e32 v39, 9, v28
	v_add_u32_e32 v153, s11, v30
	v_add_u32_e32 v154, s34, v30
	v_lshlrev_b32_e32 v30, 2, v53
	v_or_b32_e32 v55, 25, v28
	v_or_b32_e32 v57, 26, v28
	v_lshlrev_b32_e32 v28, 2, v59
	v_add_u32_e32 v155, s11, v30
	v_add_u32_e32 v156, s34, v30
	v_lshlrev_b32_e32 v30, 2, v55
	v_add_u32_e32 v161, s11, v28
	v_add_u32_e32 v162, s34, v28
	v_or_b32_e32 v28, 64, v118
	v_writelane_b32 v253, s0, 28
	v_add_u32_e32 v157, s11, v30
	v_add_u32_e32 v158, s34, v30
	v_lshlrev_b32_e32 v30, 2, v57
	v_lshrrev_b32_e32 v32, 5, v28
	v_writelane_b32 v253, s1, 29
	v_readlane_b32 s0, v252, 30
	v_add_u32_e32 v159, s11, v30
	v_add_u32_e32 v160, s34, v30
	v_mul_u32_u24_e32 v28, 0x110, v2
	v_mul_u32_u24_e32 v30, 0x110, v32
	v_lshlrev_b32_e32 v17, 2, v17
	v_add3_u32 v163, s0, v28, v17
	v_add3_u32 v164, s0, v30, v17
	v_or_b32_e32 v28, 0xc0, v118
	v_or_b32_e32 v30, 0x80, v118
	v_lshrrev_b32_e32 v36, 5, v28
	v_lshrrev_b32_e32 v34, 5, v30
	v_mul_u32_u24_e32 v28, 0x110, v34
	v_mul_u32_u24_e32 v30, 0x110, v36
	v_add3_u32 v165, s0, v28, v17
	v_add3_u32 v166, s0, v30, v17
	v_or_b32_e32 v28, 0x140, v118
	v_or_b32_e32 v30, 0x100, v118
	v_lshrrev_b32_e32 v40, 5, v28
	v_lshrrev_b32_e32 v38, 5, v30
	v_mul_u32_u24_e32 v28, 0x110, v38
	v_mul_u32_u24_e32 v30, 0x110, v40
	v_add3_u32 v167, s0, v28, v17
	v_add3_u32 v168, s0, v30, v17
	v_or_b32_e32 v28, 0x1c0, v118
	v_or_b32_e32 v30, 0x180, v118
	v_lshrrev_b32_e32 v44, 5, v28
	v_lshrrev_b32_e32 v42, 5, v30
	v_mul_u32_u24_e32 v28, 0x110, v42
	v_mul_u32_u24_e32 v30, 0x110, v44
	v_add3_u32 v169, s0, v28, v17
	v_add3_u32 v170, s0, v30, v17
	v_or_b32_e32 v28, 0x240, v118
	v_or_b32_e32 v30, 0x200, v118
	v_lshrrev_b32_e32 v48, 5, v28
	v_lshrrev_b32_e32 v46, 5, v30
	v_mul_u32_u24_e32 v28, 0x110, v46
	v_mul_u32_u24_e32 v30, 0x110, v48
	v_add3_u32 v171, s0, v28, v17
	v_add3_u32 v172, s0, v30, v17
	v_or_b32_e32 v28, 0x2c0, v118
	v_or_b32_e32 v30, 0x280, v118
	v_lshrrev_b32_e32 v52, 5, v28
	v_lshrrev_b32_e32 v50, 5, v30
	v_mul_u32_u24_e32 v28, 0x110, v50
	v_mul_u32_u24_e32 v30, 0x110, v52
	v_add3_u32 v173, s0, v28, v17
	v_add3_u32 v174, s0, v30, v17
	v_or_b32_e32 v28, 0x340, v118
	v_or_b32_e32 v30, 0x300, v118
	v_lshrrev_b32_e32 v56, 5, v28
	v_lshrrev_b32_e32 v54, 5, v30
	v_mul_u32_u24_e32 v28, 0x110, v54
	v_mul_u32_u24_e32 v30, 0x110, v56
	v_add3_u32 v175, s0, v28, v17
	v_add3_u32 v176, s0, v30, v17
	v_or_b32_e32 v28, 0x3c0, v118
	v_or_b32_e32 v30, 0x380, v118
	v_lshrrev_b32_e32 v60, 5, v28
	v_lshrrev_b32_e32 v58, 5, v30
	v_mul_u32_u24_e32 v6, 0x110, v3
	v_mul_u32_u24_e32 v28, 0x110, v58
	v_mul_u32_u24_e32 v30, 0x110, v60
	v_add3_u32 v130, s0, v6, v8
	v_add3_u32 v177, s0, v28, v17
	v_add3_u32 v178, s0, v30, v17
	s_mov_b32 s0, 0xbc00
	v_lshlrev_b32_e32 v123, 5, v15
	v_mul_lo_u32 v15, v15, s0
	s_add_i32 s0, 0, 0x100
	v_lshl_add_u32 v182, v29, 1, s0
	s_mov_b64 s[0:1], 0x1e680000
	v_lshl_add_u64 v[28:29], v[12:13], 0, s[0:1]
	v_cmp_lt_u32_e64 s[0:1], v3, v33
	v_cmp_lt_u32_e64 s[2:3], v3, v49
	v_add_u32_e32 v128, s11, v8
	v_writelane_b32 v253, s0, 48
	v_add_u32_e32 v129, s34, v8
	v_lshlrev_b32_e32 v6, 2, v31
	v_writelane_b32 v253, s1, 49
	v_cmp_lt_u32_e64 s[0:1], v3, v35
	v_lshlrev_b32_e32 v8, 2, v33
	v_lshlrev_b32_e32 v10, 2, v35
	v_writelane_b32 v253, s0, 50
	v_lshlrev_b32_e32 v14, 2, v37
	v_lshlrev_b32_e32 v16, 2, v39
	v_writelane_b32 v253, s1, 51
	v_cmp_lt_u32_e64 s[0:1], v3, v37
	v_readlane_b32 s37, v251, 2
	v_readlane_b32 s38, v251, 3
	v_writelane_b32 v253, s0, 44
	v_readlane_b32 s39, v251, 4
	v_readlane_b32 s42, v251, 7
	v_writelane_b32 v253, s1, 45
	v_cmp_lt_u32_e64 s[0:1], v3, v39
	v_readlane_b32 s43, v251, 8
	v_readlane_b32 s46, v251, 11
	v_writelane_b32 v253, s0, 46
	v_readlane_b32 s47, v251, 12
	v_lshlrev_b32_e32 v5, 1, v118
	v_writelane_b32 v253, s1, 47
	v_cmp_lt_u32_e64 s[0:1], v3, v41
	v_lshlrev_b32_e32 v9, 4, v2
	v_mad_u32_u24 v11, v3, s4, 0
	v_writelane_b32 v253, s0, 52
	v_and_b32_e32 v127, 0x7f, v4
	v_add_u32_e32 v131, s11, v6
	v_writelane_b32 v253, s1, 53
	v_cmp_lt_u32_e64 s[0:1], v3, v43
	v_add_u32_e32 v132, s34, v6
	v_lshlrev_b32_e32 v6, 6, v31
	v_writelane_b32 v253, s0, 12
	v_add_u32_e32 v133, s11, v8
	v_add_u32_e32 v134, s34, v8
	v_writelane_b32 v253, s1, 13
	v_cmp_lt_u32_e64 s[0:1], v3, v45
	v_lshlrev_b32_e32 v8, 6, v33
	v_add_u32_e32 v135, s11, v10
	v_writelane_b32 v253, s0, 14
	v_add_u32_e32 v136, s34, v10
	v_lshlrev_b32_e32 v10, 6, v35
	v_writelane_b32 v253, s1, 15
	v_cmp_lt_u32_e64 s[0:1], v3, v47
	v_add_u32_e32 v137, s11, v14
	v_add_u32_e32 v138, s34, v14
	v_writelane_b32 v253, s0, 16
	v_lshlrev_b32_e32 v14, 6, v37
	v_add_u32_e32 v139, s11, v16
	v_writelane_b32 v253, s1, 17
	v_writelane_b32 v253, s2, 18
	v_add_u32_e32 v140, s34, v16
	v_lshlrev_b32_e32 v16, 6, v39
	v_writelane_b32 v253, s3, 19
	v_cmp_lt_u32_e64 s[2:3], v3, v51
	v_lshlrev_b32_e32 v74, 6, v41
	v_lshlrev_b32_e32 v76, 6, v43
	v_writelane_b32 v254, s2, 2
	v_lshlrev_b32_e32 v78, 6, v45
	v_lshlrev_b32_e32 v80, 6, v47
	v_writelane_b32 v254, s3, 3
	v_cmp_lt_u32_e64 s[2:3], v3, v53
	v_lshlrev_b32_e32 v82, 6, v49
	v_lshlrev_b32_e32 v84, 6, v51
	v_writelane_b32 v253, s2, 62
	v_lshlrev_b32_e32 v86, 6, v53
	v_lshlrev_b32_e32 v88, 6, v55
	v_writelane_b32 v253, s3, 63
	v_cmp_lt_u32_e64 s[2:3], v3, v55
	v_lshlrev_b32_e32 v90, 6, v57
	v_lshlrev_b32_e32 v92, 6, v59
	v_writelane_b32 v254, s2, 0
	v_lshlrev_b32_e32 v4, 3, v4
	v_add_u32_e32 v119, s11, v18
	v_writelane_b32 v254, s3, 1
	v_cmp_lt_u32_e64 s[2:3], v3, v57
	v_add_u32_e32 v120, s34, v18
	v_lshl_add_u32 v19, v3, 2, s11
	v_writelane_b32 v253, s2, 58
	v_add_u32_e32 v126, 0, v125
	v_add3_u32 v179, v15, v4, 0
	v_or_b32_e32 v180, 0xffffffc0, v118
	v_lshlrev_b32_e32 v181, 3, v118
	v_lshlrev_b32_e32 v183, 2, v5
	v_lshlrev_b32_e32 v30, 1, v2
	v_lshlrev_b32_e32 v32, 1, v32
	v_lshlrev_b32_e32 v34, 1, v34
	v_lshlrev_b32_e32 v36, 1, v36
	v_lshlrev_b32_e32 v38, 1, v38
	v_lshlrev_b32_e32 v40, 1, v40
	v_lshlrev_b32_e32 v42, 1, v42
	v_lshlrev_b32_e32 v44, 1, v44
	v_lshlrev_b32_e32 v46, 1, v46
	v_lshlrev_b32_e32 v48, 1, v48
	v_lshlrev_b32_e32 v50, 1, v50
	v_lshlrev_b32_e32 v52, 1, v52
	v_lshlrev_b32_e32 v54, 1, v54
	v_lshlrev_b32_e32 v56, 1, v56
	v_lshlrev_b32_e32 v58, 1, v58
	v_lshlrev_b32_e32 v60, 1, v60
	v_add_u32_e32 v184, v7, v9
	v_add_u32_e32 v185, v11, v9
	v_lshlrev_b32_e32 v62, 1, v0
	v_lshlrev_b32_e32 v64, 1, v6
	v_lshlrev_b32_e32 v66, 1, v8
	v_lshlrev_b32_e32 v68, 1, v10
	v_lshlrev_b32_e32 v70, 1, v14
	v_lshlrev_b32_e32 v72, 1, v16
	v_lshlrev_b32_e32 v74, 1, v74
	v_lshlrev_b32_e32 v76, 1, v76
	v_lshlrev_b32_e32 v78, 1, v78
	v_lshlrev_b32_e32 v80, 1, v80
	v_lshlrev_b32_e32 v82, 1, v82
	v_lshlrev_b32_e32 v84, 1, v84
	v_lshlrev_b32_e32 v86, 1, v86
	v_lshlrev_b32_e32 v88, 1, v88
	v_lshlrev_b32_e32 v90, 1, v90
	v_lshlrev_b32_e32 v92, 1, v92
	v_cmp_le_u32_e64 s[36:37], v3, v31
	v_cmp_le_u32_e64 s[38:39], v3, v33
	v_cmp_le_u32_e64 s[42:43], v3, v35
	v_cmp_le_u32_e64 s[46:47], v3, v37
	v_cmp_le_u32_e64 s[50:51], v3, v39
	v_cmp_le_u32_e64 s[54:55], v3, v41
	v_cmp_le_u32_e64 s[72:73], v3, v43
	v_cmp_le_u32_e64 s[76:77], v3, v45
	v_cmp_le_u32_e64 s[80:81], v3, v47
	v_cmp_le_u32_e64 s[0:1], v3, v49
	v_cmp_le_u32_e64 s[74:75], v3, v51
	v_cmp_le_u32_e64 s[78:79], v3, v53
	v_cmp_le_u32_e64 s[82:83], v3, v55
	v_cmp_le_u32_e64 s[86:87], v3, v57
	v_writelane_b32 v253, s3, 59
	v_cmp_le_u32_e64 s[90:91], v3, v59
	v_cmp_lt_u32_e64 s[92:93], v3, v59
	s_mov_b64 s[28:29], 0
	v_readlane_b32 s40, v251, 5
	v_readlane_b32 s41, v251, 6
	v_readlane_b32 s44, v251, 9
	v_readlane_b32 s45, v251, 10
	v_readlane_b32 s48, v251, 13
	v_readlane_b32 s49, v251, 14
	s_branch .LBB0_768

	.amdhsa_kernel _Z10fwd_kernel6Params
		.amdhsa_group_segment_fixed_size 20480
		.amdhsa_private_segment_fixed_size 0
		.amdhsa_kernarg_size 456
		.amdhsa_user_sgpr_count 2
		.amdhsa_user_sgpr_dispatch_ptr 0
		.amdhsa_user_sgpr_queue_ptr 0
		.amdhsa_user_sgpr_kernarg_segment_ptr 1
		.amdhsa_user_sgpr_dispatch_id 0
		.amdhsa_user_sgpr_kernarg_preload_length 0
		.amdhsa_user_sgpr_kernarg_preload_offset 0
		.amdhsa_user_sgpr_private_segment_size 0
		.amdhsa_uses_dynamic_stack 0
		.amdhsa_enable_private_segment 0
		.amdhsa_system_sgpr_workgroup_id_x 1
		.amdhsa_system_sgpr_workgroup_id_y 0
		.amdhsa_system_sgpr_workgroup_id_z 0
		.amdhsa_system_sgpr_workgroup_info 0
		.amdhsa_system_vgpr_workitem_id 2
		.amdhsa_next_free_vgpr 256
		.amdhsa_next_free_sgpr 102
		.amdhsa_accum_offset 256
		.amdhsa_reserve_vcc 1
		.amdhsa_float_round_mode_32 0
		.amdhsa_float_round_mode_16_64 0
		.amdhsa_float_denorm_mode_32 3
		.amdhsa_float_denorm_mode_16_64 3
		.amdhsa_dx10_clamp 1
		.amdhsa_ieee_mode 1
		.amdhsa_fp16_overflow 0
		.amdhsa_tg_split 0
		.amdhsa_exception_fp_ieee_invalid_op 0
		.amdhsa_exception_fp_denorm_src 0
		.amdhsa_exception_fp_ieee_div_zero 0
		.amdhsa_exception_fp_ieee_overflow 0
		.amdhsa_exception_fp_ieee_underflow 0
		.amdhsa_exception_fp_ieee_inexact 0
		.amdhsa_exception_int_div_zero 0
	.end_amdhsa_kernel
